# GEMM loops: s_setprio 1 removed (all MFMA blocks run at default priority)
# speedup vs baseline: 1.0109x; 1.0109x over previous
.LBB0_217:
	ds_read_b128 v[144:147], v151
	ds_read_b128 v[154:157], v151 offset:1024
	ds_read_b128 v[158:161], v151 offset:2048
	ds_read_b128 v[162:165], v151 offset:3072
	ds_read_b128 v[166:169], v152
	ds_read_b128 v[170:173], v152 offset:1024
	ds_read_b128 v[174:177], v152 offset:2048
	ds_read_b128 v[178:181], v152 offset:3072
	s_add_u32 s26, s24, 0xfffc0080
	s_addc_u32 s27, s25, -1
	s_cmp_eq_u32 s50, 12
	s_cselect_b32 s29, s17, s27
	s_cselect_b32 s28, s46, s26
	s_cselect_b32 s27, s15, s49
	s_cselect_b32 s26, s47, s48
	v_lshl_add_u64 v[214:215], s[24:25], 0, v[136:137]
	s_add_i32 m0, s23, 0xc000
	ds_read_b128 v[182:185], v153
	ds_read_b128 v[186:189], v153 offset:1024
	ds_read_b128 v[190:193], v153 offset:2048
	ds_read_b128 v[194:197], v153 offset:3072
	ds_read_b128 v[198:201], v153 offset:4096
	ds_read_b128 v[202:205], v153 offset:5120
	ds_read_b128 v[206:209], v153 offset:6144
	ds_read_b128 v[210:213], v153 offset:7168
	global_load_lds_dwordx4 v[214:215], off
	v_lshl_add_u64 v[214:215], s[24:25], 0, v[138:139]
	s_add_i32 m0, s23, 0xe000
	s_nop 0
	global_load_lds_dwordx4 v[214:215], off
	s_waitcnt vmcnt(8)
	s_waitcnt lgkmcnt(0)
	s_barrier
	s_setprio 0
	s_waitcnt lgkmcnt(0)
	v_mfma_f32_16x16x32_bf16 v[124:127], v[144:147], v[182:185], v[124:127]
	v_mfma_f32_16x16x32_bf16 v[120:123], v[158:161], v[182:185], v[120:123]
	v_mfma_f32_16x16x32_bf16 v[108:111], v[144:147], v[190:193], v[108:111]
	v_mfma_f32_16x16x32_bf16 v[104:107], v[158:161], v[190:193], v[104:107]
	v_mfma_f32_16x16x32_bf16 v[92:95], v[144:147], v[198:201], v[92:95]
	v_mfma_f32_16x16x32_bf16 v[88:91], v[158:161], v[198:201], v[88:91]
	v_mfma_f32_16x16x32_bf16 v[76:79], v[144:147], v[206:209], v[76:79]
	v_mfma_f32_16x16x32_bf16 v[72:75], v[158:161], v[206:209], v[72:75]
	v_mfma_f32_16x16x32_bf16 v[124:127], v[154:157], v[186:189], v[124:127]
	v_mfma_f32_16x16x32_bf16 v[120:123], v[162:165], v[186:189], v[120:123]
	v_mfma_f32_16x16x32_bf16 v[108:111], v[154:157], v[194:197], v[108:111]
	v_mfma_f32_16x16x32_bf16 v[104:107], v[162:165], v[194:197], v[104:107]
	v_mfma_f32_16x16x32_bf16 v[92:95], v[154:157], v[202:205], v[92:95]
	v_mfma_f32_16x16x32_bf16 v[88:91], v[162:165], v[202:205], v[88:91]
	v_mfma_f32_16x16x32_bf16 v[76:79], v[154:157], v[210:213], v[76:79]
	v_mfma_f32_16x16x32_bf16 v[72:75], v[162:165], v[210:213], v[72:75]
	s_setprio 0
	s_setprio 0
	v_mfma_f32_16x16x32_bf16 v[116:119], v[166:169], v[182:185], v[116:119]
	v_mfma_f32_16x16x32_bf16 v[112:115], v[174:177], v[182:185], v[112:115]
	v_mfma_f32_16x16x32_bf16 v[100:103], v[166:169], v[190:193], v[100:103]
	v_mfma_f32_16x16x32_bf16 v[96:99], v[174:177], v[190:193], v[96:99]
	v_mfma_f32_16x16x32_bf16 v[84:87], v[166:169], v[198:201], v[84:87]
	v_mfma_f32_16x16x32_bf16 v[80:83], v[174:177], v[198:201], v[80:83]
	v_mfma_f32_16x16x32_bf16 v[68:71], v[166:169], v[206:209], v[68:71]
	v_mfma_f32_16x16x32_bf16 v[64:67], v[174:177], v[206:209], v[64:67]
	v_mfma_f32_16x16x32_bf16 v[116:119], v[170:173], v[186:189], v[116:119]
	v_mfma_f32_16x16x32_bf16 v[112:115], v[178:181], v[186:189], v[112:115]
	v_mfma_f32_16x16x32_bf16 v[100:103], v[170:173], v[194:197], v[100:103]
	v_mfma_f32_16x16x32_bf16 v[96:99], v[178:181], v[194:197], v[96:99]
	v_mfma_f32_16x16x32_bf16 v[84:87], v[170:173], v[202:205], v[84:87]
	v_mfma_f32_16x16x32_bf16 v[80:83], v[178:181], v[202:205], v[80:83]
	v_mfma_f32_16x16x32_bf16 v[68:71], v[170:173], v[210:213], v[68:71]
	v_mfma_f32_16x16x32_bf16 v[64:67], v[178:181], v[210:213], v[64:67]
	s_setprio 0
	s_barrier
	s_add_i32 s51, s42, s30
	v_lshl_add_u64 v[214:215], s[26:27], 0, v[132:133]
	s_mov_b32 m0, s51
	ds_read_b128 v[182:185], v153 offset:16384
	ds_read_b128 v[186:189], v153 offset:17408
	ds_read_b128 v[190:193], v153 offset:18432
	ds_read_b128 v[194:197], v153 offset:19456
	ds_read_b128 v[198:201], v153 offset:20480
	ds_read_b128 v[202:205], v153 offset:21504
	ds_read_b128 v[206:209], v153 offset:22528
	ds_read_b128 v[210:213], v153 offset:23552
	global_load_lds_dwordx4 v[214:215], off
	s_add_i32 m0, s51, 0x2000
	s_add_u32 s52, s26, 0x40000
	v_lshl_add_u64 v[216:217], s[26:27], 0, v[128:129]
	s_addc_u32 s53, s27, 0
	s_add_i32 s51, s43, s30
	global_load_lds_dwordx4 v[216:217], off
	v_lshl_add_u64 v[218:219], s[52:53], 0, v[132:133]
	s_mov_b32 m0, s51
	v_lshl_add_u64 v[220:221], s[28:29], 0, v[130:131]
	global_load_lds_dwordx4 v[218:219], off
	v_lshl_add_u64 v[218:219], s[52:53], 0, v[128:129]
	s_add_i32 m0, s51, 0x2000
	s_nop 0
	global_load_lds_dwordx4 v[218:219], off
	v_lshl_add_u64 v[218:219], s[28:29], 0, v[134:135]
	s_mov_b32 m0, s23
	s_nop 0
	global_load_lds_dwordx4 v[218:219], off
	s_mov_b32 m0, s34
	s_nop 0
	global_load_lds_dwordx4 v[220:221], off
	s_waitcnt vmcnt(8)
	s_waitcnt lgkmcnt(0)
	s_barrier
	s_setprio 0
	s_waitcnt lgkmcnt(0)
	v_mfma_f32_16x16x32_bf16 v[60:63], v[144:147], v[182:185], v[60:63]
	v_mfma_f32_16x16x32_bf16 v[56:59], v[158:161], v[182:185], v[56:59]
	v_mfma_f32_16x16x32_bf16 v[44:47], v[144:147], v[190:193], v[44:47]
	v_mfma_f32_16x16x32_bf16 v[40:43], v[158:161], v[190:193], v[40:43]
	v_mfma_f32_16x16x32_bf16 v[28:31], v[144:147], v[198:201], v[28:31]
	v_mfma_f32_16x16x32_bf16 v[24:27], v[158:161], v[198:201], v[24:27]
	v_mfma_f32_16x16x32_bf16 v[12:15], v[144:147], v[206:209], v[12:15]
	v_mfma_f32_16x16x32_bf16 v[8:11], v[158:161], v[206:209], v[8:11]
	v_mfma_f32_16x16x32_bf16 v[60:63], v[154:157], v[186:189], v[60:63]
	v_mfma_f32_16x16x32_bf16 v[56:59], v[162:165], v[186:189], v[56:59]
	v_mfma_f32_16x16x32_bf16 v[44:47], v[154:157], v[194:197], v[44:47]
	v_mfma_f32_16x16x32_bf16 v[40:43], v[162:165], v[194:197], v[40:43]
	v_mfma_f32_16x16x32_bf16 v[28:31], v[154:157], v[202:205], v[28:31]
	v_mfma_f32_16x16x32_bf16 v[24:27], v[162:165], v[202:205], v[24:27]
	v_mfma_f32_16x16x32_bf16 v[12:15], v[154:157], v[210:213], v[12:15]
	v_mfma_f32_16x16x32_bf16 v[8:11], v[162:165], v[210:213], v[8:11]
	s_setprio 0
	s_setprio 0
	v_mfma_f32_16x16x32_bf16 v[52:55], v[166:169], v[182:185], v[52:55]
	v_mfma_f32_16x16x32_bf16 v[48:51], v[174:177], v[182:185], v[48:51]
	v_mfma_f32_16x16x32_bf16 v[36:39], v[166:169], v[190:193], v[36:39]
	v_mfma_f32_16x16x32_bf16 v[32:35], v[174:177], v[190:193], v[32:35]
	v_mfma_f32_16x16x32_bf16 v[20:23], v[166:169], v[198:201], v[20:23]
	v_mfma_f32_16x16x32_bf16 v[16:19], v[174:177], v[198:201], v[16:19]
	v_mfma_f32_16x16x32_bf16 v[4:7], v[166:169], v[206:209], v[4:7]
	v_mfma_f32_16x16x32_bf16 v[0:3], v[174:177], v[206:209], v[0:3]
	v_mfma_f32_16x16x32_bf16 v[52:55], v[170:173], v[186:189], v[52:55]
	v_mfma_f32_16x16x32_bf16 v[48:51], v[178:181], v[186:189], v[48:51]
	v_mfma_f32_16x16x32_bf16 v[36:39], v[170:173], v[194:197], v[36:39]
	v_mfma_f32_16x16x32_bf16 v[32:35], v[178:181], v[194:197], v[32:35]
	v_mfma_f32_16x16x32_bf16 v[20:23], v[170:173], v[202:205], v[20:23]
	v_mfma_f32_16x16x32_bf16 v[16:19], v[178:181], v[202:205], v[16:19]
	v_mfma_f32_16x16x32_bf16 v[4:7], v[170:173], v[210:213], v[4:7]
	v_mfma_f32_16x16x32_bf16 v[0:3], v[178:181], v[210:213], v[0:3]
	s_setprio 0
	s_barrier
	s_add_i32 s51, 0, 0x18000
	s_add_i32 s52, 0, 0x1c000
	v_add_u32_e32 v162, s51, v149
	v_add_u32_e32 v178, s52, v149
	ds_read_b128 v[144:147], v162
	ds_read_b128 v[154:157], v162 offset:1024
	ds_read_b128 v[158:161], v162 offset:2048
	ds_read_b128 v[162:165], v162 offset:3072
	ds_read_b128 v[166:169], v178
	ds_read_b128 v[170:173], v178 offset:1024
	ds_read_b128 v[174:177], v178 offset:2048
	ds_read_b128 v[178:181], v178 offset:3072
	s_add_u32 s28, s28, 0x40000
	s_addc_u32 s29, s29, 0
	s_mov_b32 m0, s35
	v_lshl_add_u64 v[222:223], s[28:29], 0, v[134:135]
	ds_read_b128 v[182:185], v153 offset:32768
	ds_read_b128 v[186:189], v153 offset:33792
	ds_read_b128 v[190:193], v153 offset:34816
	ds_read_b128 v[194:197], v153 offset:35840
	ds_read_b128 v[198:201], v153 offset:36864
	ds_read_b128 v[202:205], v153 offset:37888
	ds_read_b128 v[206:209], v153 offset:38912
	ds_read_b128 v[210:213], v153 offset:39936
	global_load_lds_dwordx4 v[222:223], off
	v_lshl_add_u64 v[222:223], s[28:29], 0, v[130:131]
	s_mov_b32 m0, s36
	s_nop 0
	global_load_lds_dwordx4 v[222:223], off
	s_waitcnt vmcnt(8)
	s_waitcnt lgkmcnt(0)
	s_barrier
	s_setprio 0
	s_waitcnt lgkmcnt(0)
	v_mfma_f32_16x16x32_bf16 v[124:127], v[144:147], v[182:185], v[124:127]
	v_mfma_f32_16x16x32_bf16 v[120:123], v[158:161], v[182:185], v[120:123]
	v_mfma_f32_16x16x32_bf16 v[108:111], v[144:147], v[190:193], v[108:111]
	v_mfma_f32_16x16x32_bf16 v[104:107], v[158:161], v[190:193], v[104:107]
	v_mfma_f32_16x16x32_bf16 v[92:95], v[144:147], v[198:201], v[92:95]
	v_mfma_f32_16x16x32_bf16 v[88:91], v[158:161], v[198:201], v[88:91]
	v_mfma_f32_16x16x32_bf16 v[76:79], v[144:147], v[206:209], v[76:79]
	v_mfma_f32_16x16x32_bf16 v[72:75], v[158:161], v[206:209], v[72:75]
	v_mfma_f32_16x16x32_bf16 v[124:127], v[154:157], v[186:189], v[124:127]
	v_mfma_f32_16x16x32_bf16 v[120:123], v[162:165], v[186:189], v[120:123]
	v_mfma_f32_16x16x32_bf16 v[108:111], v[154:157], v[194:197], v[108:111]
	v_mfma_f32_16x16x32_bf16 v[104:107], v[162:165], v[194:197], v[104:107]
	v_mfma_f32_16x16x32_bf16 v[92:95], v[154:157], v[202:205], v[92:95]
	v_mfma_f32_16x16x32_bf16 v[88:91], v[162:165], v[202:205], v[88:91]
	v_mfma_f32_16x16x32_bf16 v[76:79], v[154:157], v[210:213], v[76:79]
	v_mfma_f32_16x16x32_bf16 v[72:75], v[162:165], v[210:213], v[72:75]
	s_setprio 0
	s_setprio 0
	v_mfma_f32_16x16x32_bf16 v[116:119], v[166:169], v[182:185], v[116:119]
	v_mfma_f32_16x16x32_bf16 v[112:115], v[174:177], v[182:185], v[112:115]
	v_mfma_f32_16x16x32_bf16 v[100:103], v[166:169], v[190:193], v[100:103]
	v_mfma_f32_16x16x32_bf16 v[96:99], v[174:177], v[190:193], v[96:99]
	v_mfma_f32_16x16x32_bf16 v[84:87], v[166:169], v[198:201], v[84:87]
	v_mfma_f32_16x16x32_bf16 v[80:83], v[174:177], v[198:201], v[80:83]
	v_mfma_f32_16x16x32_bf16 v[68:71], v[166:169], v[206:209], v[68:71]
	v_mfma_f32_16x16x32_bf16 v[64:67], v[174:177], v[206:209], v[64:67]
	v_mfma_f32_16x16x32_bf16 v[116:119], v[170:173], v[186:189], v[116:119]
	v_mfma_f32_16x16x32_bf16 v[112:115], v[178:181], v[186:189], v[112:115]
	v_mfma_f32_16x16x32_bf16 v[100:103], v[170:173], v[194:197], v[100:103]
	v_mfma_f32_16x16x32_bf16 v[96:99], v[178:181], v[194:197], v[96:99]
	v_mfma_f32_16x16x32_bf16 v[84:87], v[170:173], v[202:205], v[84:87]
	v_mfma_f32_16x16x32_bf16 v[80:83], v[178:181], v[202:205], v[80:83]
	v_mfma_f32_16x16x32_bf16 v[68:71], v[170:173], v[210:213], v[68:71]
	v_mfma_f32_16x16x32_bf16 v[64:67], v[178:181], v[210:213], v[64:67]
	s_setprio 0
	s_barrier
	s_add_i32 s28, s51, s30
	v_lshl_add_u64 v[214:215], v[214:215], 0, s[10:11]
	s_mov_b32 m0, s28
	ds_read_b128 v[182:185], v153 offset:49152
	ds_read_b128 v[186:189], v153 offset:50176
	ds_read_b128 v[190:193], v153 offset:51200
	ds_read_b128 v[194:197], v153 offset:52224
	ds_read_b128 v[198:201], v153 offset:53248
	ds_read_b128 v[202:205], v153 offset:54272
	ds_read_b128 v[206:209], v153 offset:55296
	ds_read_b128 v[210:213], v153 offset:56320
	global_load_lds_dwordx4 v[214:215], off
	s_add_i32 m0, s28, 0x2000
	s_add_u32 s26, s26, 0x40080
	v_lshl_add_u64 v[214:215], v[216:217], 0, s[10:11]
	s_addc_u32 s27, s27, 0
	s_add_i32 s28, s52, s30
	global_load_lds_dwordx4 v[214:215], off
	v_lshl_add_u64 v[214:215], s[26:27], 0, v[132:133]
	s_mov_b32 m0, s28
	s_nop 0
	global_load_lds_dwordx4 v[214:215], off
	v_lshl_add_u64 v[214:215], s[26:27], 0, v[128:129]
	s_add_i32 m0, s28, 0x2000
	s_nop 0
	global_load_lds_dwordx4 v[214:215], off
	v_lshl_add_u64 v[214:215], v[218:219], 0, s[10:11]
	s_mov_b32 m0, s39
	s_nop 0
	global_load_lds_dwordx4 v[214:215], off
	v_lshl_add_u64 v[214:215], v[220:221], 0, s[10:11]
	s_mov_b32 m0, s40
	s_nop 0
	global_load_lds_dwordx4 v[214:215], off
	s_waitcnt vmcnt(8)
	s_waitcnt lgkmcnt(0)
	s_barrier
	s_setprio 0
	s_waitcnt lgkmcnt(0)
	v_mfma_f32_16x16x32_bf16 v[60:63], v[144:147], v[182:185], v[60:63]
	v_mfma_f32_16x16x32_bf16 v[56:59], v[158:161], v[182:185], v[56:59]
	v_mfma_f32_16x16x32_bf16 v[44:47], v[144:147], v[190:193], v[44:47]
	v_mfma_f32_16x16x32_bf16 v[40:43], v[158:161], v[190:193], v[40:43]
	v_mfma_f32_16x16x32_bf16 v[28:31], v[144:147], v[198:201], v[28:31]
	v_mfma_f32_16x16x32_bf16 v[24:27], v[158:161], v[198:201], v[24:27]
	v_mfma_f32_16x16x32_bf16 v[12:15], v[144:147], v[206:209], v[12:15]
	v_mfma_f32_16x16x32_bf16 v[8:11], v[158:161], v[206:209], v[8:11]
	v_mfma_f32_16x16x32_bf16 v[60:63], v[154:157], v[186:189], v[60:63]
	v_mfma_f32_16x16x32_bf16 v[56:59], v[162:165], v[186:189], v[56:59]
	v_mfma_f32_16x16x32_bf16 v[44:47], v[154:157], v[194:197], v[44:47]
	v_mfma_f32_16x16x32_bf16 v[40:43], v[162:165], v[194:197], v[40:43]
	v_mfma_f32_16x16x32_bf16 v[28:31], v[154:157], v[202:205], v[28:31]
	v_mfma_f32_16x16x32_bf16 v[24:27], v[162:165], v[202:205], v[24:27]
	v_mfma_f32_16x16x32_bf16 v[12:15], v[154:157], v[210:213], v[12:15]
	v_mfma_f32_16x16x32_bf16 v[8:11], v[162:165], v[210:213], v[8:11]
	s_setprio 0
	s_setprio 0
	v_mfma_f32_16x16x32_bf16 v[52:55], v[166:169], v[182:185], v[52:55]
	v_mfma_f32_16x16x32_bf16 v[48:51], v[174:177], v[182:185], v[48:51]
	v_mfma_f32_16x16x32_bf16 v[36:39], v[166:169], v[190:193], v[36:39]
	v_mfma_f32_16x16x32_bf16 v[32:35], v[174:177], v[190:193], v[32:35]
	v_mfma_f32_16x16x32_bf16 v[20:23], v[166:169], v[198:201], v[20:23]
	v_mfma_f32_16x16x32_bf16 v[16:19], v[174:177], v[198:201], v[16:19]
	v_mfma_f32_16x16x32_bf16 v[4:7], v[166:169], v[206:209], v[4:7]
	v_mfma_f32_16x16x32_bf16 v[0:3], v[174:177], v[206:209], v[0:3]
	v_mfma_f32_16x16x32_bf16 v[52:55], v[170:173], v[186:189], v[52:55]
	v_mfma_f32_16x16x32_bf16 v[48:51], v[178:181], v[186:189], v[48:51]
	v_mfma_f32_16x16x32_bf16 v[36:39], v[170:173], v[194:197], v[36:39]
	v_mfma_f32_16x16x32_bf16 v[32:35], v[178:181], v[194:197], v[32:35]
	v_mfma_f32_16x16x32_bf16 v[20:23], v[170:173], v[202:205], v[20:23]
	v_mfma_f32_16x16x32_bf16 v[16:19], v[178:181], v[202:205], v[16:19]
	v_mfma_f32_16x16x32_bf16 v[4:7], v[170:173], v[210:213], v[4:7]
	v_mfma_f32_16x16x32_bf16 v[0:3], v[178:181], v[210:213], v[0:3]
	s_setprio 0
	s_barrier
	s_add_i32 s50, s50, 2
	s_add_u32 s24, s24, 0x100
	s_addc_u32 s25, s25, 0
	s_add_u32 s48, s48, 0x100
	s_addc_u32 s49, s49, 0
	s_cmp_gt_u32 s50, 13
	s_cbranch_scc0 .LBB0_217
	s_and_b64 vcc, exec, s[12:13]
	s_cbranch_vccz .LBB0_220
	s_barrier

.LBB0_296:
	ds_read_b128 v[144:147], v169
	ds_read_b128 v[148:151], v169 offset:1024
	ds_read_b128 v[152:155], v169 offset:2048
	ds_read_b128 v[156:159], v169 offset:3072
	ds_read_b128 v[160:163], v170
	ds_read_b128 v[172:175], v170 offset:1024
	ds_read_b128 v[176:179], v170 offset:2048
	ds_read_b128 v[180:183], v170 offset:3072
	s_add_u32 s20, s18, 0x100
	s_addc_u32 s21, s19, 0
	s_cmp_eq_u32 s48, 40
	s_cselect_b32 s25, s9, s21
	s_cselect_b32 s24, s8, s20
	s_cselect_b32 s23, s17, s47
	s_cselect_b32 s22, s16, s46
	v_lshl_add_u64 v[164:165], s[18:19], 0, v[136:137]
	s_add_i32 m0, s28, 0xc000
	ds_read_b128 v[184:187], v171
	ds_read_b128 v[188:191], v171 offset:1024
	ds_read_b128 v[192:195], v171 offset:2048
	ds_read_b128 v[196:199], v171 offset:3072
	ds_read_b128 v[200:203], v171 offset:4096
	ds_read_b128 v[204:207], v171 offset:5120
	ds_read_b128 v[208:211], v171 offset:6144
	ds_read_b128 v[212:215], v171 offset:7168
	global_load_lds_dwordx4 v[164:165], off
	v_lshl_add_u64 v[164:165], s[18:19], 0, v[138:139]
	s_add_i32 m0, s28, 0xe000
	s_nop 0
	global_load_lds_dwordx4 v[164:165], off
	s_waitcnt vmcnt(8)
	s_waitcnt lgkmcnt(0)
	s_barrier
	s_setprio 0
	s_waitcnt lgkmcnt(0)
	v_mfma_f32_16x16x32_bf16 v[124:127], v[144:147], v[184:187], v[124:127]
	v_mfma_f32_16x16x32_bf16 v[120:123], v[152:155], v[184:187], v[120:123]
	v_mfma_f32_16x16x32_bf16 v[116:119], v[144:147], v[192:195], v[116:119]
	v_mfma_f32_16x16x32_bf16 v[112:115], v[152:155], v[192:195], v[112:115]
	v_mfma_f32_16x16x32_bf16 v[96:99], v[144:147], v[200:203], v[96:99]
	v_mfma_f32_16x16x32_bf16 v[88:91], v[152:155], v[200:203], v[88:91]
	v_mfma_f32_16x16x32_bf16 v[80:83], v[144:147], v[208:211], v[80:83]
	v_mfma_f32_16x16x32_bf16 v[72:75], v[152:155], v[208:211], v[72:75]
	v_mfma_f32_16x16x32_bf16 v[124:127], v[148:151], v[188:191], v[124:127]
	v_mfma_f32_16x16x32_bf16 v[120:123], v[156:159], v[188:191], v[120:123]
	v_mfma_f32_16x16x32_bf16 v[116:119], v[148:151], v[196:199], v[116:119]
	v_mfma_f32_16x16x32_bf16 v[112:115], v[156:159], v[196:199], v[112:115]
	v_mfma_f32_16x16x32_bf16 v[96:99], v[148:151], v[204:207], v[96:99]
	v_mfma_f32_16x16x32_bf16 v[88:91], v[156:159], v[204:207], v[88:91]
	v_mfma_f32_16x16x32_bf16 v[80:83], v[148:151], v[212:215], v[80:83]
	v_mfma_f32_16x16x32_bf16 v[72:75], v[156:159], v[212:215], v[72:75]
	s_setprio 0
	s_setprio 0
	v_mfma_f32_16x16x32_bf16 v[108:111], v[160:163], v[184:187], v[108:111]
	v_mfma_f32_16x16x32_bf16 v[104:107], v[176:179], v[184:187], v[104:107]
	v_mfma_f32_16x16x32_bf16 v[100:103], v[160:163], v[192:195], v[100:103]
	v_mfma_f32_16x16x32_bf16 v[92:95], v[176:179], v[192:195], v[92:95]
	v_mfma_f32_16x16x32_bf16 v[84:87], v[160:163], v[200:203], v[84:87]
	v_mfma_f32_16x16x32_bf16 v[76:79], v[176:179], v[200:203], v[76:79]
	v_mfma_f32_16x16x32_bf16 v[68:71], v[160:163], v[208:211], v[68:71]
	v_mfma_f32_16x16x32_bf16 v[64:67], v[176:179], v[208:211], v[64:67]
	v_mfma_f32_16x16x32_bf16 v[108:111], v[172:175], v[188:191], v[108:111]
	v_mfma_f32_16x16x32_bf16 v[104:107], v[180:183], v[188:191], v[104:107]
	v_mfma_f32_16x16x32_bf16 v[100:103], v[172:175], v[196:199], v[100:103]
	v_mfma_f32_16x16x32_bf16 v[92:95], v[180:183], v[196:199], v[92:95]
	v_mfma_f32_16x16x32_bf16 v[84:87], v[172:175], v[204:207], v[84:87]
	v_mfma_f32_16x16x32_bf16 v[76:79], v[180:183], v[204:207], v[76:79]
	v_mfma_f32_16x16x32_bf16 v[68:71], v[172:175], v[212:215], v[68:71]
	v_mfma_f32_16x16x32_bf16 v[64:67], v[180:183], v[212:215], v[64:67]
	s_setprio 0
	s_barrier
	s_add_i32 s18, s40, s26
	v_lshl_add_u64 v[164:165], s[22:23], 0, v[132:133]
	s_mov_b32 m0, s18
	ds_read_b128 v[184:187], v171 offset:16384
	ds_read_b128 v[188:191], v171 offset:17408
	ds_read_b128 v[192:195], v171 offset:18432
	ds_read_b128 v[196:199], v171 offset:19456
	ds_read_b128 v[200:203], v171 offset:20480
	ds_read_b128 v[204:207], v171 offset:21504
	ds_read_b128 v[208:211], v171 offset:22528
	ds_read_b128 v[212:215], v171 offset:23552
	global_load_lds_dwordx4 v[164:165], off
	s_add_i32 m0, s18, 0x2000
	s_add_u32 s18, s22, 0xb0000
	v_lshl_add_u64 v[216:217], s[22:23], 0, v[128:129]
	s_addc_u32 s19, s23, 0
	s_add_i32 s49, s41, s26
	global_load_lds_dwordx4 v[216:217], off
	v_lshl_add_u64 v[218:219], s[18:19], 0, v[132:133]
	s_mov_b32 m0, s49
	v_lshl_add_u64 v[220:221], s[24:25], 0, v[130:131]
	global_load_lds_dwordx4 v[218:219], off
	v_lshl_add_u64 v[218:219], s[18:19], 0, v[128:129]
	s_add_i32 m0, s49, 0x2000
	s_nop 0
	global_load_lds_dwordx4 v[218:219], off
	v_lshl_add_u64 v[218:219], s[24:25], 0, v[134:135]
	s_mov_b32 m0, s28
	s_nop 0
	global_load_lds_dwordx4 v[218:219], off
	s_mov_b32 m0, s29
	s_nop 0
	global_load_lds_dwordx4 v[220:221], off
	s_waitcnt vmcnt(8)
	s_waitcnt lgkmcnt(0)
	s_barrier
	s_setprio 0
	s_waitcnt lgkmcnt(0)
	v_mfma_f32_16x16x32_bf16 v[60:63], v[144:147], v[184:187], v[60:63]
	v_mfma_f32_16x16x32_bf16 v[56:59], v[152:155], v[184:187], v[56:59]
	v_mfma_f32_16x16x32_bf16 v[48:51], v[144:147], v[192:195], v[48:51]
	v_mfma_f32_16x16x32_bf16 v[40:43], v[152:155], v[192:195], v[40:43]
	v_mfma_f32_16x16x32_bf16 v[32:35], v[144:147], v[200:203], v[32:35]
	v_mfma_f32_16x16x32_bf16 v[24:27], v[152:155], v[200:203], v[24:27]
	v_mfma_f32_16x16x32_bf16 v[16:19], v[144:147], v[208:211], v[16:19]
	v_mfma_f32_16x16x32_bf16 v[8:11], v[152:155], v[208:211], v[8:11]
	v_mfma_f32_16x16x32_bf16 v[60:63], v[148:151], v[188:191], v[60:63]
	v_mfma_f32_16x16x32_bf16 v[56:59], v[156:159], v[188:191], v[56:59]
	v_mfma_f32_16x16x32_bf16 v[48:51], v[148:151], v[196:199], v[48:51]
	v_mfma_f32_16x16x32_bf16 v[40:43], v[156:159], v[196:199], v[40:43]
	v_mfma_f32_16x16x32_bf16 v[32:35], v[148:151], v[204:207], v[32:35]
	v_mfma_f32_16x16x32_bf16 v[24:27], v[156:159], v[204:207], v[24:27]
	v_mfma_f32_16x16x32_bf16 v[16:19], v[148:151], v[212:215], v[16:19]
	v_mfma_f32_16x16x32_bf16 v[8:11], v[156:159], v[212:215], v[8:11]
	s_setprio 0
	s_setprio 0
	v_mfma_f32_16x16x32_bf16 v[52:55], v[160:163], v[184:187], v[52:55]
	v_mfma_f32_16x16x32_bf16 v[44:47], v[176:179], v[184:187], v[44:47]
	v_mfma_f32_16x16x32_bf16 v[36:39], v[160:163], v[192:195], v[36:39]
	v_mfma_f32_16x16x32_bf16 v[28:31], v[176:179], v[192:195], v[28:31]
	v_mfma_f32_16x16x32_bf16 v[20:23], v[160:163], v[200:203], v[20:23]
	v_mfma_f32_16x16x32_bf16 v[12:15], v[176:179], v[200:203], v[12:15]
	v_mfma_f32_16x16x32_bf16 v[4:7], v[160:163], v[208:211], v[4:7]
	v_mfma_f32_16x16x32_bf16 v[0:3], v[176:179], v[208:211], v[0:3]
	v_mfma_f32_16x16x32_bf16 v[52:55], v[172:175], v[188:191], v[52:55]
	v_mfma_f32_16x16x32_bf16 v[44:47], v[180:183], v[188:191], v[44:47]
	v_mfma_f32_16x16x32_bf16 v[36:39], v[172:175], v[196:199], v[36:39]
	v_mfma_f32_16x16x32_bf16 v[28:31], v[180:183], v[196:199], v[28:31]
	v_mfma_f32_16x16x32_bf16 v[20:23], v[172:175], v[204:207], v[20:23]
	v_mfma_f32_16x16x32_bf16 v[12:15], v[180:183], v[204:207], v[12:15]
	v_mfma_f32_16x16x32_bf16 v[4:7], v[172:175], v[212:215], v[4:7]
	v_mfma_f32_16x16x32_bf16 v[0:3], v[180:183], v[212:215], v[0:3]
	s_setprio 0
	s_barrier
	s_add_i32 s49, 0, 0x18000
	s_add_i32 s50, 0, 0x1c000
	v_add_u32_e32 v156, s49, v167
	v_add_u32_e32 v180, s50, v167
	ds_read_b128 v[144:147], v156
	ds_read_b128 v[148:151], v156 offset:1024
	ds_read_b128 v[152:155], v156 offset:2048
	ds_read_b128 v[156:159], v156 offset:3072
	ds_read_b128 v[160:163], v180
	ds_read_b128 v[172:175], v180 offset:1024
	ds_read_b128 v[176:179], v180 offset:2048
	ds_read_b128 v[180:183], v180 offset:3072
	s_add_u32 s18, s24, 0xb0000
	s_addc_u32 s19, s25, 0
	s_mov_b32 m0, s30
	v_lshl_add_u64 v[222:223], s[18:19], 0, v[134:135]
	ds_read_b128 v[184:187], v171 offset:32768
	ds_read_b128 v[188:191], v171 offset:33792
	ds_read_b128 v[192:195], v171 offset:34816
	ds_read_b128 v[196:199], v171 offset:35840
	ds_read_b128 v[200:203], v171 offset:36864
	ds_read_b128 v[204:207], v171 offset:37888
	ds_read_b128 v[208:211], v171 offset:38912
	ds_read_b128 v[212:215], v171 offset:39936
	global_load_lds_dwordx4 v[222:223], off
	v_lshl_add_u64 v[222:223], s[18:19], 0, v[130:131]
	s_mov_b32 m0, s31
	s_nop 0
	global_load_lds_dwordx4 v[222:223], off
	s_waitcnt vmcnt(8)
	s_waitcnt lgkmcnt(0)
	s_barrier
	s_setprio 0
	s_waitcnt lgkmcnt(0)
	v_mfma_f32_16x16x32_bf16 v[124:127], v[144:147], v[184:187], v[124:127]
	v_mfma_f32_16x16x32_bf16 v[120:123], v[152:155], v[184:187], v[120:123]
	v_mfma_f32_16x16x32_bf16 v[116:119], v[144:147], v[192:195], v[116:119]
	v_mfma_f32_16x16x32_bf16 v[112:115], v[152:155], v[192:195], v[112:115]
	v_mfma_f32_16x16x32_bf16 v[96:99], v[144:147], v[200:203], v[96:99]
	v_mfma_f32_16x16x32_bf16 v[88:91], v[152:155], v[200:203], v[88:91]
	v_mfma_f32_16x16x32_bf16 v[80:83], v[144:147], v[208:211], v[80:83]
	v_mfma_f32_16x16x32_bf16 v[72:75], v[152:155], v[208:211], v[72:75]
	v_mfma_f32_16x16x32_bf16 v[124:127], v[148:151], v[188:191], v[124:127]
	v_mfma_f32_16x16x32_bf16 v[120:123], v[156:159], v[188:191], v[120:123]
	v_mfma_f32_16x16x32_bf16 v[116:119], v[148:151], v[196:199], v[116:119]
	v_mfma_f32_16x16x32_bf16 v[112:115], v[156:159], v[196:199], v[112:115]
	v_mfma_f32_16x16x32_bf16 v[96:99], v[148:151], v[204:207], v[96:99]
	v_mfma_f32_16x16x32_bf16 v[88:91], v[156:159], v[204:207], v[88:91]
	v_mfma_f32_16x16x32_bf16 v[80:83], v[148:151], v[212:215], v[80:83]
	v_mfma_f32_16x16x32_bf16 v[72:75], v[156:159], v[212:215], v[72:75]
	s_setprio 0
	s_setprio 0
	v_mfma_f32_16x16x32_bf16 v[108:111], v[160:163], v[184:187], v[108:111]
	v_mfma_f32_16x16x32_bf16 v[104:107], v[176:179], v[184:187], v[104:107]
	v_mfma_f32_16x16x32_bf16 v[100:103], v[160:163], v[192:195], v[100:103]
	v_mfma_f32_16x16x32_bf16 v[92:95], v[176:179], v[192:195], v[92:95]
	v_mfma_f32_16x16x32_bf16 v[84:87], v[160:163], v[200:203], v[84:87]
	v_mfma_f32_16x16x32_bf16 v[76:79], v[176:179], v[200:203], v[76:79]
	v_mfma_f32_16x16x32_bf16 v[68:71], v[160:163], v[208:211], v[68:71]
	v_mfma_f32_16x16x32_bf16 v[64:67], v[176:179], v[208:211], v[64:67]
	v_mfma_f32_16x16x32_bf16 v[108:111], v[172:175], v[188:191], v[108:111]
	v_mfma_f32_16x16x32_bf16 v[104:107], v[180:183], v[188:191], v[104:107]
	v_mfma_f32_16x16x32_bf16 v[100:103], v[172:175], v[196:199], v[100:103]
	v_mfma_f32_16x16x32_bf16 v[92:95], v[180:183], v[196:199], v[92:95]
	v_mfma_f32_16x16x32_bf16 v[84:87], v[172:175], v[204:207], v[84:87]
	v_mfma_f32_16x16x32_bf16 v[76:79], v[180:183], v[204:207], v[76:79]
	v_mfma_f32_16x16x32_bf16 v[68:71], v[172:175], v[212:215], v[68:71]
	v_mfma_f32_16x16x32_bf16 v[64:67], v[180:183], v[212:215], v[64:67]
	s_setprio 0
	s_barrier
	s_add_i32 s18, s49, s26
	v_lshl_add_u64 v[164:165], v[164:165], 0, s[12:13]
	s_mov_b32 m0, s18
	ds_read_b128 v[184:187], v171 offset:49152
	ds_read_b128 v[188:191], v171 offset:50176
	ds_read_b128 v[192:195], v171 offset:51200
	ds_read_b128 v[196:199], v171 offset:52224
	ds_read_b128 v[200:203], v171 offset:53248
	ds_read_b128 v[204:207], v171 offset:54272
	ds_read_b128 v[208:211], v171 offset:55296
	ds_read_b128 v[212:215], v171 offset:56320
	global_load_lds_dwordx4 v[164:165], off
	s_add_i32 m0, s18, 0x2000
	s_add_u32 s18, s22, 0xb0080
	v_lshl_add_u64 v[164:165], v[216:217], 0, s[12:13]
	s_addc_u32 s19, s23, 0
	s_add_i32 s22, s50, s26
	global_load_lds_dwordx4 v[164:165], off
	v_lshl_add_u64 v[164:165], s[18:19], 0, v[132:133]
	s_mov_b32 m0, s22
	s_nop 0
	global_load_lds_dwordx4 v[164:165], off
	v_lshl_add_u64 v[164:165], s[18:19], 0, v[128:129]
	s_add_i32 m0, s22, 0x2000
	s_nop 0
	global_load_lds_dwordx4 v[164:165], off
	v_lshl_add_u64 v[164:165], v[218:219], 0, s[12:13]
	s_mov_b32 m0, s37
	s_nop 0
	global_load_lds_dwordx4 v[164:165], off
	v_lshl_add_u64 v[164:165], v[220:221], 0, s[12:13]
	s_mov_b32 m0, s38
	s_nop 0
	global_load_lds_dwordx4 v[164:165], off
	s_waitcnt vmcnt(8)
	s_waitcnt lgkmcnt(0)
	s_barrier
	s_setprio 0
	s_waitcnt lgkmcnt(0)
	v_mfma_f32_16x16x32_bf16 v[60:63], v[144:147], v[184:187], v[60:63]
	v_mfma_f32_16x16x32_bf16 v[56:59], v[152:155], v[184:187], v[56:59]
	v_mfma_f32_16x16x32_bf16 v[48:51], v[144:147], v[192:195], v[48:51]
	v_mfma_f32_16x16x32_bf16 v[40:43], v[152:155], v[192:195], v[40:43]
	v_mfma_f32_16x16x32_bf16 v[32:35], v[144:147], v[200:203], v[32:35]
	v_mfma_f32_16x16x32_bf16 v[24:27], v[152:155], v[200:203], v[24:27]
	v_mfma_f32_16x16x32_bf16 v[16:19], v[144:147], v[208:211], v[16:19]
	v_mfma_f32_16x16x32_bf16 v[8:11], v[152:155], v[208:211], v[8:11]
	v_mfma_f32_16x16x32_bf16 v[60:63], v[148:151], v[188:191], v[60:63]
	v_mfma_f32_16x16x32_bf16 v[56:59], v[156:159], v[188:191], v[56:59]
	v_mfma_f32_16x16x32_bf16 v[48:51], v[148:151], v[196:199], v[48:51]
	v_mfma_f32_16x16x32_bf16 v[40:43], v[156:159], v[196:199], v[40:43]
	v_mfma_f32_16x16x32_bf16 v[32:35], v[148:151], v[204:207], v[32:35]
	v_mfma_f32_16x16x32_bf16 v[24:27], v[156:159], v[204:207], v[24:27]
	v_mfma_f32_16x16x32_bf16 v[16:19], v[148:151], v[212:215], v[16:19]
	v_mfma_f32_16x16x32_bf16 v[8:11], v[156:159], v[212:215], v[8:11]
	s_setprio 0
	s_setprio 0
	v_mfma_f32_16x16x32_bf16 v[52:55], v[160:163], v[184:187], v[52:55]
	v_mfma_f32_16x16x32_bf16 v[44:47], v[176:179], v[184:187], v[44:47]
	v_mfma_f32_16x16x32_bf16 v[36:39], v[160:163], v[192:195], v[36:39]
	v_mfma_f32_16x16x32_bf16 v[28:31], v[176:179], v[192:195], v[28:31]
	v_mfma_f32_16x16x32_bf16 v[20:23], v[160:163], v[200:203], v[20:23]
	v_mfma_f32_16x16x32_bf16 v[12:15], v[176:179], v[200:203], v[12:15]
	v_mfma_f32_16x16x32_bf16 v[4:7], v[160:163], v[208:211], v[4:7]
	v_mfma_f32_16x16x32_bf16 v[0:3], v[176:179], v[208:211], v[0:3]
	v_mfma_f32_16x16x32_bf16 v[52:55], v[172:175], v[188:191], v[52:55]
	v_mfma_f32_16x16x32_bf16 v[44:47], v[180:183], v[188:191], v[44:47]
	v_mfma_f32_16x16x32_bf16 v[36:39], v[172:175], v[196:199], v[36:39]
	v_mfma_f32_16x16x32_bf16 v[28:31], v[180:183], v[196:199], v[28:31]
	v_mfma_f32_16x16x32_bf16 v[20:23], v[172:175], v[204:207], v[20:23]
	v_mfma_f32_16x16x32_bf16 v[12:15], v[180:183], v[204:207], v[12:15]
	v_mfma_f32_16x16x32_bf16 v[4:7], v[172:175], v[212:215], v[4:7]
	v_mfma_f32_16x16x32_bf16 v[0:3], v[180:183], v[212:215], v[0:3]
	s_setprio 0
	s_barrier
	s_add_i32 s48, s48, 2
	s_add_u32 s46, s46, 0x100
	s_addc_u32 s47, s47, 0
	s_cmp_gt_u32 s48, 41
	s_mov_b64 s[18:19], s[20:21]
	s_cbranch_scc0 .LBB0_296
	s_and_b64 vcc, exec, s[14:15]
	s_cbranch_vccz .LBB0_299
	s_barrier

.LBB0_433:
	ds_read_b128 v[130:133], v239
	ds_read_b128 v[134:137], v239 offset:1024
	ds_read_b128 v[138:141], v239 offset:2048
	ds_read_b128 v[142:145], v239 offset:3072
	ds_read_b128 v[146:149], v240
	ds_read_b128 v[150:153], v240 offset:1024
	ds_read_b128 v[154:157], v240 offset:2048
	ds_read_b128 v[158:161], v240 offset:3072
	s_add_u32 s30, s28, 0xfffc0080
	s_addc_u32 s31, s29, -1
	s_cmp_eq_u32 s58, 12
	s_cselect_b32 s35, s9, s31
	s_cselect_b32 s34, s23, s30
	s_cselect_b32 s31, s21, s57
	s_cselect_b32 s30, s55, s56
	v_lshl_add_u64 v[80:81], s[28:29], 0, v[222:223]
	s_add_i32 m0, s36, 0xc000
	ds_read_b128 v[162:165], v241
	ds_read_b128 v[166:169], v241 offset:1024
	ds_read_b128 v[170:173], v241 offset:2048
	ds_read_b128 v[174:177], v241 offset:3072
	ds_read_b128 v[178:181], v241 offset:4096
	ds_read_b128 v[182:185], v241 offset:5120
	ds_read_b128 v[186:189], v241 offset:6144
	ds_read_b128 v[190:193], v241 offset:7168
	global_load_lds_dwordx4 v[80:81], off
	v_lshl_add_u64 v[80:81], s[28:29], 0, v[224:225]
	s_add_i32 m0, s36, 0xe000
	s_nop 0
	global_load_lds_dwordx4 v[80:81], off
	s_waitcnt vmcnt(8)
	s_waitcnt lgkmcnt(0)
	s_barrier
	s_setprio 0
	s_waitcnt lgkmcnt(0)
	v_mfma_f32_16x16x32_bf16 v[126:129], v[130:133], v[162:165], v[126:129]
	v_mfma_f32_16x16x32_bf16 v[122:125], v[138:141], v[162:165], v[122:125]
	v_mfma_f32_16x16x32_bf16 v[110:113], v[130:133], v[170:173], v[110:113]
	v_mfma_f32_16x16x32_bf16 v[106:109], v[138:141], v[170:173], v[106:109]
	v_mfma_f32_16x16x32_bf16 v[94:97], v[130:133], v[178:181], v[94:97]
	v_mfma_f32_16x16x32_bf16 v[90:93], v[138:141], v[178:181], v[90:93]
	v_mfma_f32_16x16x32_bf16 v[76:79], v[130:133], v[186:189], v[76:79]
	v_mfma_f32_16x16x32_bf16 v[72:75], v[138:141], v[186:189], v[72:75]
	v_mfma_f32_16x16x32_bf16 v[126:129], v[134:137], v[166:169], v[126:129]
	v_mfma_f32_16x16x32_bf16 v[122:125], v[142:145], v[166:169], v[122:125]
	v_mfma_f32_16x16x32_bf16 v[110:113], v[134:137], v[174:177], v[110:113]
	v_mfma_f32_16x16x32_bf16 v[106:109], v[142:145], v[174:177], v[106:109]
	v_mfma_f32_16x16x32_bf16 v[94:97], v[134:137], v[182:185], v[94:97]
	v_mfma_f32_16x16x32_bf16 v[90:93], v[142:145], v[182:185], v[90:93]
	v_mfma_f32_16x16x32_bf16 v[76:79], v[134:137], v[190:193], v[76:79]
	v_mfma_f32_16x16x32_bf16 v[72:75], v[142:145], v[190:193], v[72:75]
	s_setprio 0
	s_setprio 0
	v_mfma_f32_16x16x32_bf16 v[118:121], v[146:149], v[162:165], v[118:121]
	v_mfma_f32_16x16x32_bf16 v[114:117], v[154:157], v[162:165], v[114:117]
	v_mfma_f32_16x16x32_bf16 v[102:105], v[146:149], v[170:173], v[102:105]
	v_mfma_f32_16x16x32_bf16 v[98:101], v[154:157], v[170:173], v[98:101]
	v_mfma_f32_16x16x32_bf16 v[86:89], v[146:149], v[178:181], v[86:89]
	v_mfma_f32_16x16x32_bf16 v[80:83], v[154:157], v[178:181], v[82:85]
	v_mfma_f32_16x16x32_bf16 v[68:71], v[146:149], v[186:189], v[68:71]
	v_mfma_f32_16x16x32_bf16 v[64:67], v[154:157], v[186:189], v[64:67]
	v_mfma_f32_16x16x32_bf16 v[118:121], v[150:153], v[166:169], v[118:121]
	v_mfma_f32_16x16x32_bf16 v[114:117], v[158:161], v[166:169], v[114:117]
	v_mfma_f32_16x16x32_bf16 v[102:105], v[150:153], v[174:177], v[102:105]
	v_mfma_f32_16x16x32_bf16 v[98:101], v[158:161], v[174:177], v[98:101]
	v_mfma_f32_16x16x32_bf16 v[86:89], v[150:153], v[182:185], v[86:89]
	v_mfma_f32_16x16x32_bf16 v[80:83], v[158:161], v[182:185], v[80:83]
	v_mfma_f32_16x16x32_bf16 v[68:71], v[150:153], v[190:193], v[68:71]
	v_mfma_f32_16x16x32_bf16 v[64:67], v[158:161], v[190:193], v[64:67]
	s_setprio 0
	s_barrier
	s_add_i32 s59, s50, s33
	v_lshl_add_u64 v[194:195], s[30:31], 0, v[212:213]
	s_mov_b32 m0, s59
	ds_read_b128 v[162:165], v241 offset:16384
	ds_read_b128 v[166:169], v241 offset:17408
	ds_read_b128 v[170:173], v241 offset:18432
	ds_read_b128 v[174:177], v241 offset:19456
	ds_read_b128 v[178:181], v241 offset:20480
	ds_read_b128 v[182:185], v241 offset:21504
	ds_read_b128 v[186:189], v241 offset:22528
	ds_read_b128 v[190:193], v241 offset:23552
	global_load_lds_dwordx4 v[194:195], off
	s_add_i32 m0, s59, 0x2000
	s_add_u32 s60, s30, 0x40000
	v_lshl_add_u64 v[196:197], s[30:31], 0, v[216:217]
	s_addc_u32 s61, s31, 0
	s_add_i32 s59, s51, s33
	global_load_lds_dwordx4 v[196:197], off
	v_lshl_add_u64 v[84:85], s[60:61], 0, v[212:213]
	s_mov_b32 m0, s59
	v_lshl_add_u64 v[198:199], s[34:35], 0, v[210:211]
	global_load_lds_dwordx4 v[84:85], off
	v_lshl_add_u64 v[84:85], s[60:61], 0, v[216:217]
	s_add_i32 m0, s59, 0x2000
	v_lshl_add_u64 v[200:201], s[34:35], 0, v[214:215]
	global_load_lds_dwordx4 v[84:85], off
	s_mov_b32 m0, s36
	s_nop 0
	global_load_lds_dwordx4 v[198:199], off
	s_mov_b32 m0, s37
	s_nop 0
	global_load_lds_dwordx4 v[200:201], off
	s_waitcnt vmcnt(8)
	s_waitcnt lgkmcnt(0)
	s_barrier
	s_setprio 0
	s_waitcnt lgkmcnt(0)
	v_mfma_f32_16x16x32_bf16 v[60:63], v[130:133], v[162:165], v[60:63]
	v_mfma_f32_16x16x32_bf16 v[56:59], v[138:141], v[162:165], v[56:59]
	v_mfma_f32_16x16x32_bf16 v[44:47], v[130:133], v[170:173], v[44:47]
	v_mfma_f32_16x16x32_bf16 v[40:43], v[138:141], v[170:173], v[40:43]
	v_mfma_f32_16x16x32_bf16 v[28:31], v[130:133], v[178:181], v[28:31]
	v_mfma_f32_16x16x32_bf16 v[24:27], v[138:141], v[178:181], v[24:27]
	v_mfma_f32_16x16x32_bf16 v[12:15], v[130:133], v[186:189], v[12:15]
	v_mfma_f32_16x16x32_bf16 v[8:11], v[138:141], v[186:189], v[8:11]
	v_mfma_f32_16x16x32_bf16 v[60:63], v[134:137], v[166:169], v[60:63]
	v_mfma_f32_16x16x32_bf16 v[56:59], v[142:145], v[166:169], v[56:59]
	v_mfma_f32_16x16x32_bf16 v[44:47], v[134:137], v[174:177], v[44:47]
	v_mfma_f32_16x16x32_bf16 v[40:43], v[142:145], v[174:177], v[40:43]
	v_mfma_f32_16x16x32_bf16 v[28:31], v[134:137], v[182:185], v[28:31]
	v_mfma_f32_16x16x32_bf16 v[24:27], v[142:145], v[182:185], v[24:27]
	v_mfma_f32_16x16x32_bf16 v[12:15], v[134:137], v[190:193], v[12:15]
	v_mfma_f32_16x16x32_bf16 v[8:11], v[142:145], v[190:193], v[8:11]
	s_setprio 0
	s_setprio 0
	v_mfma_f32_16x16x32_bf16 v[52:55], v[146:149], v[162:165], v[52:55]
	v_mfma_f32_16x16x32_bf16 v[48:51], v[154:157], v[162:165], v[48:51]
	v_mfma_f32_16x16x32_bf16 v[36:39], v[146:149], v[170:173], v[36:39]
	v_mfma_f32_16x16x32_bf16 v[32:35], v[154:157], v[170:173], v[32:35]
	v_mfma_f32_16x16x32_bf16 v[20:23], v[146:149], v[178:181], v[20:23]
	v_mfma_f32_16x16x32_bf16 v[16:19], v[154:157], v[178:181], v[16:19]
	v_mfma_f32_16x16x32_bf16 v[4:7], v[146:149], v[186:189], v[4:7]
	v_mfma_f32_16x16x32_bf16 v[0:3], v[154:157], v[186:189], v[0:3]
	v_mfma_f32_16x16x32_bf16 v[52:55], v[150:153], v[166:169], v[52:55]
	v_mfma_f32_16x16x32_bf16 v[48:51], v[158:161], v[166:169], v[48:51]
	v_mfma_f32_16x16x32_bf16 v[36:39], v[150:153], v[174:177], v[36:39]
	v_mfma_f32_16x16x32_bf16 v[32:35], v[158:161], v[174:177], v[32:35]
	v_mfma_f32_16x16x32_bf16 v[20:23], v[150:153], v[182:185], v[20:23]
	v_mfma_f32_16x16x32_bf16 v[16:19], v[158:161], v[182:185], v[16:19]
	v_mfma_f32_16x16x32_bf16 v[4:7], v[150:153], v[190:193], v[4:7]
	v_mfma_f32_16x16x32_bf16 v[0:3], v[158:161], v[190:193], v[0:3]
	s_setprio 0
	s_barrier
	s_add_i32 s59, 0, 0x18000
	v_add_u32_e32 v84, s59, v237
	s_add_i32 s60, 0, 0x1c000
	ds_read_b128 v[130:133], v84
	ds_read_b128 v[134:137], v84 offset:1024
	ds_read_b128 v[138:141], v84 offset:2048
	ds_read_b128 v[142:145], v84 offset:3072
	v_add_u32_e32 v84, s60, v237
	ds_read_b128 v[146:149], v84
	ds_read_b128 v[150:153], v84 offset:1024
	ds_read_b128 v[154:157], v84 offset:2048
	ds_read_b128 v[158:161], v84 offset:3072
	s_add_u32 s34, s34, 0x40000
	s_addc_u32 s35, s35, 0
	s_mov_b32 m0, s38
	v_lshl_add_u64 v[84:85], s[34:35], 0, v[210:211]
	ds_read_b128 v[162:165], v241 offset:32768
	ds_read_b128 v[166:169], v241 offset:33792
	ds_read_b128 v[170:173], v241 offset:34816
	ds_read_b128 v[174:177], v241 offset:35840
	ds_read_b128 v[178:181], v241 offset:36864
	ds_read_b128 v[182:185], v241 offset:37888
	ds_read_b128 v[186:189], v241 offset:38912
	ds_read_b128 v[190:193], v241 offset:39936
	global_load_lds_dwordx4 v[84:85], off
	v_lshl_add_u64 v[84:85], s[34:35], 0, v[214:215]
	s_mov_b32 m0, s39
	s_nop 0
	global_load_lds_dwordx4 v[84:85], off
	s_waitcnt vmcnt(8)
	s_waitcnt lgkmcnt(0)
	s_barrier
	s_setprio 0
	s_waitcnt lgkmcnt(0)
	v_mfma_f32_16x16x32_bf16 v[126:129], v[130:133], v[162:165], v[126:129]
	v_mfma_f32_16x16x32_bf16 v[122:125], v[138:141], v[162:165], v[122:125]
	v_mfma_f32_16x16x32_bf16 v[110:113], v[130:133], v[170:173], v[110:113]
	v_mfma_f32_16x16x32_bf16 v[106:109], v[138:141], v[170:173], v[106:109]
	v_mfma_f32_16x16x32_bf16 v[94:97], v[130:133], v[178:181], v[94:97]
	v_mfma_f32_16x16x32_bf16 v[90:93], v[138:141], v[178:181], v[90:93]
	v_mfma_f32_16x16x32_bf16 v[76:79], v[130:133], v[186:189], v[76:79]
	v_mfma_f32_16x16x32_bf16 v[72:75], v[138:141], v[186:189], v[72:75]
	v_mfma_f32_16x16x32_bf16 v[126:129], v[134:137], v[166:169], v[126:129]
	v_mfma_f32_16x16x32_bf16 v[122:125], v[142:145], v[166:169], v[122:125]
	v_mfma_f32_16x16x32_bf16 v[110:113], v[134:137], v[174:177], v[110:113]
	v_mfma_f32_16x16x32_bf16 v[106:109], v[142:145], v[174:177], v[106:109]
	v_mfma_f32_16x16x32_bf16 v[94:97], v[134:137], v[182:185], v[94:97]
	v_mfma_f32_16x16x32_bf16 v[90:93], v[142:145], v[182:185], v[90:93]
	v_mfma_f32_16x16x32_bf16 v[76:79], v[134:137], v[190:193], v[76:79]
	v_mfma_f32_16x16x32_bf16 v[72:75], v[142:145], v[190:193], v[72:75]
	s_setprio 0
	s_setprio 0
	v_mfma_f32_16x16x32_bf16 v[118:121], v[146:149], v[162:165], v[118:121]
	v_mfma_f32_16x16x32_bf16 v[114:117], v[154:157], v[162:165], v[114:117]
	v_mfma_f32_16x16x32_bf16 v[102:105], v[146:149], v[170:173], v[102:105]
	v_mfma_f32_16x16x32_bf16 v[98:101], v[154:157], v[170:173], v[98:101]
	v_mfma_f32_16x16x32_bf16 v[84:87], v[146:149], v[178:181], v[86:89]
	v_mfma_f32_16x16x32_bf16 v[80:83], v[154:157], v[178:181], v[80:83]
	v_mfma_f32_16x16x32_bf16 v[68:71], v[146:149], v[186:189], v[68:71]
	v_mfma_f32_16x16x32_bf16 v[64:67], v[154:157], v[186:189], v[64:67]
	v_mfma_f32_16x16x32_bf16 v[118:121], v[150:153], v[166:169], v[118:121]
	v_mfma_f32_16x16x32_bf16 v[114:117], v[158:161], v[166:169], v[114:117]
	v_mfma_f32_16x16x32_bf16 v[102:105], v[150:153], v[174:177], v[102:105]
	v_mfma_f32_16x16x32_bf16 v[98:101], v[158:161], v[174:177], v[98:101]
	v_mfma_f32_16x16x32_bf16 v[86:89], v[150:153], v[182:185], v[84:87]
	v_mfma_f32_16x16x32_bf16 v[82:85], v[158:161], v[182:185], v[80:83]
	v_mfma_f32_16x16x32_bf16 v[68:71], v[150:153], v[190:193], v[68:71]
	v_mfma_f32_16x16x32_bf16 v[64:67], v[158:161], v[190:193], v[64:67]
	s_setprio 0
	s_barrier
	s_add_i32 s34, s59, s33
	v_lshl_add_u64 v[80:81], v[194:195], 0, s[16:17]
	s_mov_b32 m0, s34
	ds_read_b128 v[162:165], v241 offset:49152
	ds_read_b128 v[166:169], v241 offset:50176
	ds_read_b128 v[170:173], v241 offset:51200
	ds_read_b128 v[174:177], v241 offset:52224
	ds_read_b128 v[178:181], v241 offset:53248
	ds_read_b128 v[182:185], v241 offset:54272
	ds_read_b128 v[186:189], v241 offset:55296
	ds_read_b128 v[190:193], v241 offset:56320
	global_load_lds_dwordx4 v[80:81], off
	s_add_i32 m0, s34, 0x2000
	s_add_u32 s30, s30, 0x40080
	v_lshl_add_u64 v[80:81], v[196:197], 0, s[16:17]
	s_addc_u32 s31, s31, 0
	s_add_i32 s34, s60, s33
	global_load_lds_dwordx4 v[80:81], off
	v_lshl_add_u64 v[80:81], s[30:31], 0, v[212:213]
	s_mov_b32 m0, s34
	s_nop 0
	global_load_lds_dwordx4 v[80:81], off
	v_lshl_add_u64 v[80:81], s[30:31], 0, v[216:217]
	s_add_i32 m0, s34, 0x2000
	s_nop 0
	global_load_lds_dwordx4 v[80:81], off
	v_lshl_add_u64 v[80:81], v[198:199], 0, s[16:17]
	s_mov_b32 m0, s47
	s_nop 0
	global_load_lds_dwordx4 v[80:81], off
	v_lshl_add_u64 v[80:81], v[200:201], 0, s[16:17]
	s_mov_b32 m0, s48
	s_nop 0
	global_load_lds_dwordx4 v[80:81], off
	s_waitcnt vmcnt(8)
	s_waitcnt lgkmcnt(0)
	s_barrier
	s_setprio 0
	s_waitcnt lgkmcnt(0)
	v_mfma_f32_16x16x32_bf16 v[60:63], v[130:133], v[162:165], v[60:63]
	v_mfma_f32_16x16x32_bf16 v[56:59], v[138:141], v[162:165], v[56:59]
	v_mfma_f32_16x16x32_bf16 v[44:47], v[130:133], v[170:173], v[44:47]
	v_mfma_f32_16x16x32_bf16 v[40:43], v[138:141], v[170:173], v[40:43]
	v_mfma_f32_16x16x32_bf16 v[28:31], v[130:133], v[178:181], v[28:31]
	v_mfma_f32_16x16x32_bf16 v[24:27], v[138:141], v[178:181], v[24:27]
	v_mfma_f32_16x16x32_bf16 v[12:15], v[130:133], v[186:189], v[12:15]
	v_mfma_f32_16x16x32_bf16 v[8:11], v[138:141], v[186:189], v[8:11]
	v_mfma_f32_16x16x32_bf16 v[60:63], v[134:137], v[166:169], v[60:63]
	v_mfma_f32_16x16x32_bf16 v[56:59], v[142:145], v[166:169], v[56:59]
	v_mfma_f32_16x16x32_bf16 v[44:47], v[134:137], v[174:177], v[44:47]
	v_mfma_f32_16x16x32_bf16 v[40:43], v[142:145], v[174:177], v[40:43]
	v_mfma_f32_16x16x32_bf16 v[28:31], v[134:137], v[182:185], v[28:31]
	v_mfma_f32_16x16x32_bf16 v[24:27], v[142:145], v[182:185], v[24:27]
	v_mfma_f32_16x16x32_bf16 v[12:15], v[134:137], v[190:193], v[12:15]
	v_mfma_f32_16x16x32_bf16 v[8:11], v[142:145], v[190:193], v[8:11]
	s_setprio 0
	s_setprio 0
	v_mfma_f32_16x16x32_bf16 v[52:55], v[146:149], v[162:165], v[52:55]
	v_mfma_f32_16x16x32_bf16 v[48:51], v[154:157], v[162:165], v[48:51]
	v_mfma_f32_16x16x32_bf16 v[36:39], v[146:149], v[170:173], v[36:39]
	v_mfma_f32_16x16x32_bf16 v[32:35], v[154:157], v[170:173], v[32:35]
	v_mfma_f32_16x16x32_bf16 v[20:23], v[146:149], v[178:181], v[20:23]
	v_mfma_f32_16x16x32_bf16 v[16:19], v[154:157], v[178:181], v[16:19]
	v_mfma_f32_16x16x32_bf16 v[4:7], v[146:149], v[186:189], v[4:7]
	v_mfma_f32_16x16x32_bf16 v[0:3], v[154:157], v[186:189], v[0:3]
	v_mfma_f32_16x16x32_bf16 v[52:55], v[150:153], v[166:169], v[52:55]
	v_mfma_f32_16x16x32_bf16 v[48:51], v[158:161], v[166:169], v[48:51]
	v_mfma_f32_16x16x32_bf16 v[36:39], v[150:153], v[174:177], v[36:39]
	v_mfma_f32_16x16x32_bf16 v[32:35], v[158:161], v[174:177], v[32:35]
	v_mfma_f32_16x16x32_bf16 v[20:23], v[150:153], v[182:185], v[20:23]
	v_mfma_f32_16x16x32_bf16 v[16:19], v[158:161], v[182:185], v[16:19]
	v_mfma_f32_16x16x32_bf16 v[4:7], v[150:153], v[190:193], v[4:7]
	v_mfma_f32_16x16x32_bf16 v[0:3], v[158:161], v[190:193], v[0:3]
	s_setprio 0
	s_barrier
	s_add_i32 s58, s58, 2
	s_add_u32 s28, s28, 0x100
	s_addc_u32 s29, s29, 0
	s_add_u32 s56, s56, 0x100
	s_addc_u32 s57, s57, 0
	s_cmp_gt_u32 s58, 13
	s_cbranch_scc0 .LBB0_433
	s_and_b64 vcc, exec, s[18:19]
	s_cbranch_vccnz .LBB0_438
	v_lshl_add_u32 v234, s10, 8, v221
	s_cmp_gt_i32 s8, 3
	s_mov_b64 s[28:29], -1
	s_cbranch_scc1 .LBB0_439

.LBB0_1026:
	ds_read_b128 v[128:131], v187
	ds_read_b128 v[132:135], v187 offset:1024
	ds_read_b128 v[152:155], v187 offset:2048
	ds_read_b128 v[156:159], v187 offset:3072
	ds_read_b128 v[160:163], v188
	ds_read_b128 v[164:167], v188 offset:1024
	ds_read_b128 v[168:171], v188 offset:2048
	ds_read_b128 v[172:175], v188 offset:3072
	s_add_u32 s36, s34, 0xfffc0080
	s_addc_u32 s37, s35, -1
	s_cmp_eq_u32 s58, 12
	s_cselect_b32 s39, s23, s37
	s_cselect_b32 s38, s29, s36
	s_cselect_b32 s37, s21, s57
	s_cselect_b32 s36, s55, s56
	v_lshl_add_u64 v[216:217], s[34:35], 0, v[144:145]
	s_add_i32 m0, s31, 0xc000
	ds_read_b128 v[176:179], v189
	ds_read_b128 v[180:183], v189 offset:1024
	ds_read_b128 v[192:195], v189 offset:2048
	ds_read_b128 v[196:199], v189 offset:3072
	ds_read_b128 v[200:203], v189 offset:4096
	ds_read_b128 v[204:207], v189 offset:5120
	ds_read_b128 v[208:211], v189 offset:6144
	ds_read_b128 v[212:215], v189 offset:7168
	global_load_lds_dwordx4 v[216:217], off
	v_lshl_add_u64 v[216:217], s[34:35], 0, v[146:147]
	s_add_i32 m0, s31, 0xe000
	s_nop 0
	global_load_lds_dwordx4 v[216:217], off
	s_waitcnt vmcnt(8)
	s_waitcnt lgkmcnt(0)
	s_barrier
	s_setprio 0
	s_waitcnt lgkmcnt(0)
	v_mfma_f32_16x16x32_bf16 v[124:127], v[128:131], v[176:179], v[124:127]
	v_mfma_f32_16x16x32_bf16 v[120:123], v[152:155], v[176:179], v[120:123]
	v_mfma_f32_16x16x32_bf16 v[108:111], v[128:131], v[192:195], v[108:111]
	v_mfma_f32_16x16x32_bf16 v[104:107], v[152:155], v[192:195], v[104:107]
	v_mfma_f32_16x16x32_bf16 v[92:95], v[128:131], v[200:203], v[92:95]
	v_mfma_f32_16x16x32_bf16 v[88:91], v[152:155], v[200:203], v[88:91]
	v_mfma_f32_16x16x32_bf16 v[76:79], v[128:131], v[208:211], v[76:79]
	v_mfma_f32_16x16x32_bf16 v[72:75], v[152:155], v[208:211], v[72:75]
	v_mfma_f32_16x16x32_bf16 v[124:127], v[132:135], v[180:183], v[124:127]
	v_mfma_f32_16x16x32_bf16 v[120:123], v[156:159], v[180:183], v[120:123]
	v_mfma_f32_16x16x32_bf16 v[108:111], v[132:135], v[196:199], v[108:111]
	v_mfma_f32_16x16x32_bf16 v[104:107], v[156:159], v[196:199], v[104:107]
	v_mfma_f32_16x16x32_bf16 v[92:95], v[132:135], v[204:207], v[92:95]
	v_mfma_f32_16x16x32_bf16 v[88:91], v[156:159], v[204:207], v[88:91]
	v_mfma_f32_16x16x32_bf16 v[76:79], v[132:135], v[212:215], v[76:79]
	v_mfma_f32_16x16x32_bf16 v[72:75], v[156:159], v[212:215], v[72:75]
	s_setprio 0
	s_setprio 0
	v_mfma_f32_16x16x32_bf16 v[116:119], v[160:163], v[176:179], v[116:119]
	v_mfma_f32_16x16x32_bf16 v[112:115], v[168:171], v[176:179], v[112:115]
	v_mfma_f32_16x16x32_bf16 v[100:103], v[160:163], v[192:195], v[100:103]
	v_mfma_f32_16x16x32_bf16 v[96:99], v[168:171], v[192:195], v[96:99]
	v_mfma_f32_16x16x32_bf16 v[84:87], v[160:163], v[200:203], v[84:87]
	v_mfma_f32_16x16x32_bf16 v[80:83], v[168:171], v[200:203], v[80:83]
	v_mfma_f32_16x16x32_bf16 v[68:71], v[160:163], v[208:211], v[68:71]
	v_mfma_f32_16x16x32_bf16 v[64:67], v[168:171], v[208:211], v[64:67]
	v_mfma_f32_16x16x32_bf16 v[116:119], v[164:167], v[180:183], v[116:119]
	v_mfma_f32_16x16x32_bf16 v[112:115], v[172:175], v[180:183], v[112:115]
	v_mfma_f32_16x16x32_bf16 v[100:103], v[164:167], v[196:199], v[100:103]
	v_mfma_f32_16x16x32_bf16 v[96:99], v[172:175], v[196:199], v[96:99]
	v_mfma_f32_16x16x32_bf16 v[84:87], v[164:167], v[204:207], v[84:87]
	v_mfma_f32_16x16x32_bf16 v[80:83], v[172:175], v[204:207], v[80:83]
	v_mfma_f32_16x16x32_bf16 v[68:71], v[164:167], v[212:215], v[68:71]
	v_mfma_f32_16x16x32_bf16 v[64:67], v[172:175], v[212:215], v[64:67]
	s_setprio 0
	s_barrier
	s_add_i32 s59, s53, s33
	v_lshl_add_u64 v[216:217], s[36:37], 0, v[138:139]
	s_mov_b32 m0, s59
	ds_read_b128 v[176:179], v189 offset:16384
	ds_read_b128 v[180:183], v189 offset:17408
	ds_read_b128 v[192:195], v189 offset:18432
	ds_read_b128 v[196:199], v189 offset:19456
	ds_read_b128 v[200:203], v189 offset:20480
	ds_read_b128 v[204:207], v189 offset:21504
	ds_read_b128 v[208:211], v189 offset:22528
	ds_read_b128 v[212:215], v189 offset:23552
	global_load_lds_dwordx4 v[216:217], off
	s_add_i32 m0, s59, 0x2000
	s_add_u32 s60, s36, 0x40000
	v_lshl_add_u64 v[218:219], s[36:37], 0, v[142:143]
	s_addc_u32 s61, s37, 0
	s_add_i32 s59, s54, s33
	global_load_lds_dwordx4 v[218:219], off
	v_lshl_add_u64 v[220:221], s[60:61], 0, v[138:139]
	s_mov_b32 m0, s59
	v_lshl_add_u64 v[222:223], s[38:39], 0, v[140:141]
	global_load_lds_dwordx4 v[220:221], off
	v_lshl_add_u64 v[220:221], s[60:61], 0, v[142:143]
	s_add_i32 m0, s59, 0x2000
	s_nop 0
	global_load_lds_dwordx4 v[220:221], off
	v_lshl_add_u64 v[220:221], s[38:39], 0, v[136:137]
	s_mov_b32 m0, s31
	s_nop 0
	global_load_lds_dwordx4 v[220:221], off
	s_mov_b32 m0, s40
	s_nop 0
	global_load_lds_dwordx4 v[222:223], off
	s_waitcnt vmcnt(8)
	s_waitcnt lgkmcnt(0)
	s_barrier
	s_setprio 0
	s_waitcnt lgkmcnt(0)
	v_mfma_f32_16x16x32_bf16 v[60:63], v[128:131], v[176:179], v[60:63]
	v_mfma_f32_16x16x32_bf16 v[56:59], v[152:155], v[176:179], v[56:59]
	v_mfma_f32_16x16x32_bf16 v[44:47], v[128:131], v[192:195], v[44:47]
	v_mfma_f32_16x16x32_bf16 v[40:43], v[152:155], v[192:195], v[40:43]
	v_mfma_f32_16x16x32_bf16 v[28:31], v[128:131], v[200:203], v[28:31]
	v_mfma_f32_16x16x32_bf16 v[24:27], v[152:155], v[200:203], v[24:27]
	v_mfma_f32_16x16x32_bf16 v[12:15], v[128:131], v[208:211], v[12:15]
	v_mfma_f32_16x16x32_bf16 v[8:11], v[152:155], v[208:211], v[8:11]
	v_mfma_f32_16x16x32_bf16 v[60:63], v[132:135], v[180:183], v[60:63]
	v_mfma_f32_16x16x32_bf16 v[56:59], v[156:159], v[180:183], v[56:59]
	v_mfma_f32_16x16x32_bf16 v[44:47], v[132:135], v[196:199], v[44:47]
	v_mfma_f32_16x16x32_bf16 v[40:43], v[156:159], v[196:199], v[40:43]
	v_mfma_f32_16x16x32_bf16 v[28:31], v[132:135], v[204:207], v[28:31]
	v_mfma_f32_16x16x32_bf16 v[24:27], v[156:159], v[204:207], v[24:27]
	v_mfma_f32_16x16x32_bf16 v[12:15], v[132:135], v[212:215], v[12:15]
	v_mfma_f32_16x16x32_bf16 v[8:11], v[156:159], v[212:215], v[8:11]
	s_setprio 0
	s_setprio 0
	v_mfma_f32_16x16x32_bf16 v[52:55], v[160:163], v[176:179], v[52:55]
	v_mfma_f32_16x16x32_bf16 v[48:51], v[168:171], v[176:179], v[48:51]
	v_mfma_f32_16x16x32_bf16 v[36:39], v[160:163], v[192:195], v[36:39]
	v_mfma_f32_16x16x32_bf16 v[32:35], v[168:171], v[192:195], v[32:35]
	v_mfma_f32_16x16x32_bf16 v[20:23], v[160:163], v[200:203], v[20:23]
	v_mfma_f32_16x16x32_bf16 v[16:19], v[168:171], v[200:203], v[16:19]
	v_mfma_f32_16x16x32_bf16 v[4:7], v[160:163], v[208:211], v[4:7]
	v_mfma_f32_16x16x32_bf16 v[0:3], v[168:171], v[208:211], v[0:3]
	v_mfma_f32_16x16x32_bf16 v[52:55], v[164:167], v[180:183], v[52:55]
	v_mfma_f32_16x16x32_bf16 v[48:51], v[172:175], v[180:183], v[48:51]
	v_mfma_f32_16x16x32_bf16 v[36:39], v[164:167], v[196:199], v[36:39]
	v_mfma_f32_16x16x32_bf16 v[32:35], v[172:175], v[196:199], v[32:35]
	v_mfma_f32_16x16x32_bf16 v[20:23], v[164:167], v[204:207], v[20:23]
	v_mfma_f32_16x16x32_bf16 v[16:19], v[172:175], v[204:207], v[16:19]
	v_mfma_f32_16x16x32_bf16 v[4:7], v[164:167], v[212:215], v[4:7]
	v_mfma_f32_16x16x32_bf16 v[0:3], v[172:175], v[212:215], v[0:3]
	s_setprio 0
	s_barrier
	s_add_i32 s59, 0, 0x18000
	s_add_i32 s60, 0, 0x1c000
	v_add_u32_e32 v156, s59, v185
	v_add_u32_e32 v172, s60, v185
	ds_read_b128 v[128:131], v156
	ds_read_b128 v[132:135], v156 offset:1024
	ds_read_b128 v[152:155], v156 offset:2048
	ds_read_b128 v[156:159], v156 offset:3072
	ds_read_b128 v[160:163], v172
	ds_read_b128 v[164:167], v172 offset:1024
	ds_read_b128 v[168:171], v172 offset:2048
	ds_read_b128 v[172:175], v172 offset:3072
	s_add_u32 s38, s38, 0x40000
	s_addc_u32 s39, s39, 0
	s_mov_b32 m0, s41
	v_lshl_add_u64 v[224:225], s[38:39], 0, v[136:137]
	ds_read_b128 v[176:179], v189 offset:32768
	ds_read_b128 v[180:183], v189 offset:33792
	ds_read_b128 v[192:195], v189 offset:34816
	ds_read_b128 v[196:199], v189 offset:35840
	ds_read_b128 v[200:203], v189 offset:36864
	ds_read_b128 v[204:207], v189 offset:37888
	ds_read_b128 v[208:211], v189 offset:38912
	ds_read_b128 v[212:215], v189 offset:39936
	global_load_lds_dwordx4 v[224:225], off
	v_lshl_add_u64 v[224:225], s[38:39], 0, v[140:141]
	s_mov_b32 m0, s42
	s_nop 0
	global_load_lds_dwordx4 v[224:225], off
	s_waitcnt vmcnt(8)
	s_waitcnt lgkmcnt(0)
	s_barrier
	s_setprio 0
	s_waitcnt lgkmcnt(0)
	v_mfma_f32_16x16x32_bf16 v[124:127], v[128:131], v[176:179], v[124:127]
	v_mfma_f32_16x16x32_bf16 v[120:123], v[152:155], v[176:179], v[120:123]
	v_mfma_f32_16x16x32_bf16 v[108:111], v[128:131], v[192:195], v[108:111]
	v_mfma_f32_16x16x32_bf16 v[104:107], v[152:155], v[192:195], v[104:107]
	v_mfma_f32_16x16x32_bf16 v[92:95], v[128:131], v[200:203], v[92:95]
	v_mfma_f32_16x16x32_bf16 v[88:91], v[152:155], v[200:203], v[88:91]
	v_mfma_f32_16x16x32_bf16 v[76:79], v[128:131], v[208:211], v[76:79]
	v_mfma_f32_16x16x32_bf16 v[72:75], v[152:155], v[208:211], v[72:75]
	v_mfma_f32_16x16x32_bf16 v[124:127], v[132:135], v[180:183], v[124:127]
	v_mfma_f32_16x16x32_bf16 v[120:123], v[156:159], v[180:183], v[120:123]
	v_mfma_f32_16x16x32_bf16 v[108:111], v[132:135], v[196:199], v[108:111]
	v_mfma_f32_16x16x32_bf16 v[104:107], v[156:159], v[196:199], v[104:107]
	v_mfma_f32_16x16x32_bf16 v[92:95], v[132:135], v[204:207], v[92:95]
	v_mfma_f32_16x16x32_bf16 v[88:91], v[156:159], v[204:207], v[88:91]
	v_mfma_f32_16x16x32_bf16 v[76:79], v[132:135], v[212:215], v[76:79]
	v_mfma_f32_16x16x32_bf16 v[72:75], v[156:159], v[212:215], v[72:75]
	s_setprio 0
	s_setprio 0
	v_mfma_f32_16x16x32_bf16 v[116:119], v[160:163], v[176:179], v[116:119]
	v_mfma_f32_16x16x32_bf16 v[112:115], v[168:171], v[176:179], v[112:115]
	v_mfma_f32_16x16x32_bf16 v[100:103], v[160:163], v[192:195], v[100:103]
	v_mfma_f32_16x16x32_bf16 v[96:99], v[168:171], v[192:195], v[96:99]
	v_mfma_f32_16x16x32_bf16 v[84:87], v[160:163], v[200:203], v[84:87]
	v_mfma_f32_16x16x32_bf16 v[80:83], v[168:171], v[200:203], v[80:83]
	v_mfma_f32_16x16x32_bf16 v[68:71], v[160:163], v[208:211], v[68:71]
	v_mfma_f32_16x16x32_bf16 v[64:67], v[168:171], v[208:211], v[64:67]
	v_mfma_f32_16x16x32_bf16 v[116:119], v[164:167], v[180:183], v[116:119]
	v_mfma_f32_16x16x32_bf16 v[112:115], v[172:175], v[180:183], v[112:115]
	v_mfma_f32_16x16x32_bf16 v[100:103], v[164:167], v[196:199], v[100:103]
	v_mfma_f32_16x16x32_bf16 v[96:99], v[172:175], v[196:199], v[96:99]
	v_mfma_f32_16x16x32_bf16 v[84:87], v[164:167], v[204:207], v[84:87]
	v_mfma_f32_16x16x32_bf16 v[80:83], v[172:175], v[204:207], v[80:83]
	v_mfma_f32_16x16x32_bf16 v[68:71], v[164:167], v[212:215], v[68:71]
	v_mfma_f32_16x16x32_bf16 v[64:67], v[172:175], v[212:215], v[64:67]
	s_setprio 0
	s_barrier
	s_add_i32 s38, s59, s33
	v_lshl_add_u64 v[216:217], v[216:217], 0, s[16:17]
	s_mov_b32 m0, s38
	ds_read_b128 v[176:179], v189 offset:49152
	ds_read_b128 v[180:183], v189 offset:50176
	ds_read_b128 v[192:195], v189 offset:51200
	ds_read_b128 v[196:199], v189 offset:52224
	ds_read_b128 v[200:203], v189 offset:53248
	ds_read_b128 v[204:207], v189 offset:54272
	ds_read_b128 v[208:211], v189 offset:55296
	ds_read_b128 v[212:215], v189 offset:56320
	global_load_lds_dwordx4 v[216:217], off
	s_add_i32 m0, s38, 0x2000
	s_add_u32 s36, s36, 0x40080
	v_lshl_add_u64 v[216:217], v[218:219], 0, s[16:17]
	s_addc_u32 s37, s37, 0
	s_add_i32 s38, s60, s33
	global_load_lds_dwordx4 v[216:217], off
	v_lshl_add_u64 v[216:217], s[36:37], 0, v[138:139]
	s_mov_b32 m0, s38
	s_nop 0
	global_load_lds_dwordx4 v[216:217], off
	v_lshl_add_u64 v[216:217], s[36:37], 0, v[142:143]
	s_add_i32 m0, s38, 0x2000
	s_nop 0
	global_load_lds_dwordx4 v[216:217], off
	v_lshl_add_u64 v[216:217], v[220:221], 0, s[16:17]
	s_mov_b32 m0, s48
	s_nop 0
	global_load_lds_dwordx4 v[216:217], off
	v_lshl_add_u64 v[216:217], v[222:223], 0, s[16:17]
	s_mov_b32 m0, s49
	s_nop 0
	global_load_lds_dwordx4 v[216:217], off
	s_waitcnt vmcnt(8)
	s_waitcnt lgkmcnt(0)
	s_barrier
	s_setprio 0
	s_waitcnt lgkmcnt(0)
	v_mfma_f32_16x16x32_bf16 v[60:63], v[128:131], v[176:179], v[60:63]
	v_mfma_f32_16x16x32_bf16 v[56:59], v[152:155], v[176:179], v[56:59]
	v_mfma_f32_16x16x32_bf16 v[44:47], v[128:131], v[192:195], v[44:47]
	v_mfma_f32_16x16x32_bf16 v[40:43], v[152:155], v[192:195], v[40:43]
	v_mfma_f32_16x16x32_bf16 v[28:31], v[128:131], v[200:203], v[28:31]
	v_mfma_f32_16x16x32_bf16 v[24:27], v[152:155], v[200:203], v[24:27]
	v_mfma_f32_16x16x32_bf16 v[12:15], v[128:131], v[208:211], v[12:15]
	v_mfma_f32_16x16x32_bf16 v[8:11], v[152:155], v[208:211], v[8:11]
	v_mfma_f32_16x16x32_bf16 v[60:63], v[132:135], v[180:183], v[60:63]
	v_mfma_f32_16x16x32_bf16 v[56:59], v[156:159], v[180:183], v[56:59]
	v_mfma_f32_16x16x32_bf16 v[44:47], v[132:135], v[196:199], v[44:47]
	v_mfma_f32_16x16x32_bf16 v[40:43], v[156:159], v[196:199], v[40:43]
	v_mfma_f32_16x16x32_bf16 v[28:31], v[132:135], v[204:207], v[28:31]
	v_mfma_f32_16x16x32_bf16 v[24:27], v[156:159], v[204:207], v[24:27]
	v_mfma_f32_16x16x32_bf16 v[12:15], v[132:135], v[212:215], v[12:15]
	v_mfma_f32_16x16x32_bf16 v[8:11], v[156:159], v[212:215], v[8:11]
	s_setprio 0
	s_setprio 0
	v_mfma_f32_16x16x32_bf16 v[52:55], v[160:163], v[176:179], v[52:55]
	v_mfma_f32_16x16x32_bf16 v[48:51], v[168:171], v[176:179], v[48:51]
	v_mfma_f32_16x16x32_bf16 v[36:39], v[160:163], v[192:195], v[36:39]
	v_mfma_f32_16x16x32_bf16 v[32:35], v[168:171], v[192:195], v[32:35]
	v_mfma_f32_16x16x32_bf16 v[20:23], v[160:163], v[200:203], v[20:23]
	v_mfma_f32_16x16x32_bf16 v[16:19], v[168:171], v[200:203], v[16:19]
	v_mfma_f32_16x16x32_bf16 v[4:7], v[160:163], v[208:211], v[4:7]
	v_mfma_f32_16x16x32_bf16 v[0:3], v[168:171], v[208:211], v[0:3]
	v_mfma_f32_16x16x32_bf16 v[52:55], v[164:167], v[180:183], v[52:55]
	v_mfma_f32_16x16x32_bf16 v[48:51], v[172:175], v[180:183], v[48:51]
	v_mfma_f32_16x16x32_bf16 v[36:39], v[164:167], v[196:199], v[36:39]
	v_mfma_f32_16x16x32_bf16 v[32:35], v[172:175], v[196:199], v[32:35]
	v_mfma_f32_16x16x32_bf16 v[20:23], v[164:167], v[204:207], v[20:23]
	v_mfma_f32_16x16x32_bf16 v[16:19], v[172:175], v[204:207], v[16:19]
	v_mfma_f32_16x16x32_bf16 v[4:7], v[164:167], v[212:215], v[4:7]
	v_mfma_f32_16x16x32_bf16 v[0:3], v[172:175], v[212:215], v[0:3]
	s_setprio 0
	s_barrier
	s_add_i32 s58, s58, 2
	s_add_u32 s34, s34, 0x100
	s_addc_u32 s35, s35, 0
	s_add_u32 s56, s56, 0x100
	s_addc_u32 s57, s57, 0
	s_cmp_gt_u32 s58, 13
	s_cbranch_scc0 .LBB0_1026
	s_and_b64 vcc, exec, s[18:19]
	s_cbranch_vccz .LBB0_1029
	s_barrier

.LBB0_1113:
	ds_read_b128 v[124:127], v171
	ds_read_b128 v[132:135], v171 offset:1024
	ds_read_b128 v[136:139], v171 offset:2048
	ds_read_b128 v[140:143], v171 offset:3072
	ds_read_b128 v[162:165], v175
	ds_read_b128 v[182:185], v175 offset:1024
	ds_read_b128 v[186:189], v175 offset:2048
	ds_read_b128 v[190:193], v175 offset:3072
	s_add_u32 s26, s24, 0xfffc0080
	s_addc_u32 s27, s25, -1
	s_cmp_eq_u32 s55, 12
	s_cselect_b32 s29, s17, s27
	s_cselect_b32 s28, s51, s26
	s_cselect_b32 s27, s15, s54
	s_cselect_b32 s26, s52, s53
	v_lshl_add_u64 v[172:173], s[24:25], 0, v[152:153]
	s_add_i32 m0, s23, 0xc000
	ds_read_b128 v[194:197], v179
	ds_read_b128 v[198:201], v179 offset:1024
	ds_read_b128 v[202:205], v179 offset:2048
	ds_read_b128 v[206:209], v179 offset:3072
	ds_read_b128 v[210:213], v179 offset:4096
	ds_read_b128 v[214:217], v179 offset:5120
	ds_read_b128 v[218:221], v179 offset:6144
	ds_read_b128 v[222:225], v179 offset:7168
	global_load_lds_dwordx4 v[172:173], off
	v_lshl_add_u64 v[172:173], s[24:25], 0, v[154:155]
	s_add_i32 m0, s23, 0xe000
	s_nop 0
	global_load_lds_dwordx4 v[172:173], off
	s_waitcnt vmcnt(8)
	s_waitcnt lgkmcnt(0)
	s_barrier
	s_setprio 0
	s_waitcnt lgkmcnt(0)
	v_mfma_f32_16x16x32_bf16 v[128:131], v[124:127], v[194:197], v[128:131]
	v_mfma_f32_16x16x32_bf16 v[120:123], v[136:139], v[194:197], v[120:123]
	v_mfma_f32_16x16x32_bf16 v[108:111], v[124:127], v[202:205], v[108:111]
	v_mfma_f32_16x16x32_bf16 v[104:107], v[136:139], v[202:205], v[104:107]
	v_mfma_f32_16x16x32_bf16 v[92:95], v[124:127], v[210:213], v[92:95]
	v_mfma_f32_16x16x32_bf16 v[88:91], v[136:139], v[210:213], v[88:91]
	v_mfma_f32_16x16x32_bf16 v[76:79], v[124:127], v[218:221], v[76:79]
	v_mfma_f32_16x16x32_bf16 v[72:75], v[136:139], v[218:221], v[72:75]
	v_mfma_f32_16x16x32_bf16 v[128:131], v[132:135], v[198:201], v[128:131]
	v_mfma_f32_16x16x32_bf16 v[120:123], v[140:143], v[198:201], v[120:123]
	v_mfma_f32_16x16x32_bf16 v[108:111], v[132:135], v[206:209], v[108:111]
	v_mfma_f32_16x16x32_bf16 v[104:107], v[140:143], v[206:209], v[104:107]
	v_mfma_f32_16x16x32_bf16 v[92:95], v[132:135], v[214:217], v[92:95]
	v_mfma_f32_16x16x32_bf16 v[88:91], v[140:143], v[214:217], v[88:91]
	v_mfma_f32_16x16x32_bf16 v[76:79], v[132:135], v[222:225], v[76:79]
	v_mfma_f32_16x16x32_bf16 v[72:75], v[140:143], v[222:225], v[72:75]
	s_setprio 0
	s_setprio 0
	v_mfma_f32_16x16x32_bf16 v[116:119], v[162:165], v[194:197], v[116:119]
	v_mfma_f32_16x16x32_bf16 v[112:115], v[186:189], v[194:197], v[112:115]
	v_mfma_f32_16x16x32_bf16 v[100:103], v[162:165], v[202:205], v[100:103]
	v_mfma_f32_16x16x32_bf16 v[96:99], v[186:189], v[202:205], v[96:99]
	v_mfma_f32_16x16x32_bf16 v[84:87], v[162:165], v[210:213], v[84:87]
	v_mfma_f32_16x16x32_bf16 v[80:83], v[186:189], v[210:213], v[80:83]
	v_mfma_f32_16x16x32_bf16 v[68:71], v[162:165], v[218:221], v[68:71]
	v_mfma_f32_16x16x32_bf16 v[64:67], v[186:189], v[218:221], v[64:67]
	v_mfma_f32_16x16x32_bf16 v[116:119], v[182:185], v[198:201], v[116:119]
	v_mfma_f32_16x16x32_bf16 v[112:115], v[190:193], v[198:201], v[112:115]
	v_mfma_f32_16x16x32_bf16 v[100:103], v[182:185], v[206:209], v[100:103]
	v_mfma_f32_16x16x32_bf16 v[96:99], v[190:193], v[206:209], v[96:99]
	v_mfma_f32_16x16x32_bf16 v[84:87], v[182:185], v[214:217], v[84:87]
	v_mfma_f32_16x16x32_bf16 v[80:83], v[190:193], v[214:217], v[80:83]
	v_mfma_f32_16x16x32_bf16 v[68:71], v[182:185], v[222:225], v[68:71]
	v_mfma_f32_16x16x32_bf16 v[64:67], v[190:193], v[222:225], v[64:67]
	s_setprio 0
	s_barrier
	s_add_i32 s56, s46, s33
	v_lshl_add_u64 v[172:173], s[26:27], 0, v[148:149]
	s_mov_b32 m0, s56
	ds_read_b128 v[194:197], v179 offset:16384
	ds_read_b128 v[198:201], v179 offset:17408
	ds_read_b128 v[202:205], v179 offset:18432
	ds_read_b128 v[206:209], v179 offset:19456
	ds_read_b128 v[210:213], v179 offset:20480
	ds_read_b128 v[214:217], v179 offset:21504
	ds_read_b128 v[218:221], v179 offset:22528
	ds_read_b128 v[222:225], v179 offset:23552
	global_load_lds_dwordx4 v[172:173], off
	s_add_i32 m0, s56, 0x2000
	s_add_u32 s56, s26, 0x40000
	v_lshl_add_u64 v[176:177], s[26:27], 0, v[144:145]
	s_addc_u32 s57, s27, 0
	s_add_i32 s58, s47, s33
	global_load_lds_dwordx4 v[176:177], off
	v_lshl_add_u64 v[226:227], s[56:57], 0, v[148:149]
	s_mov_b32 m0, s58
	v_lshl_add_u64 v[228:229], s[28:29], 0, v[146:147]
	global_load_lds_dwordx4 v[226:227], off
	v_lshl_add_u64 v[226:227], s[56:57], 0, v[144:145]
	s_add_i32 m0, s58, 0x2000
	s_nop 0
	global_load_lds_dwordx4 v[226:227], off
	v_lshl_add_u64 v[226:227], s[28:29], 0, v[150:151]
	s_mov_b32 m0, s23
	s_nop 0
	global_load_lds_dwordx4 v[226:227], off
	s_mov_b32 m0, s36
	s_nop 0
	global_load_lds_dwordx4 v[228:229], off
	s_waitcnt vmcnt(8)
	s_waitcnt lgkmcnt(0)
	s_barrier
	s_setprio 0
	s_waitcnt lgkmcnt(0)
	v_mfma_f32_16x16x32_bf16 v[60:63], v[124:127], v[194:197], v[60:63]
	v_mfma_f32_16x16x32_bf16 v[56:59], v[136:139], v[194:197], v[56:59]
	v_mfma_f32_16x16x32_bf16 v[44:47], v[124:127], v[202:205], v[44:47]
	v_mfma_f32_16x16x32_bf16 v[40:43], v[136:139], v[202:205], v[40:43]
	v_mfma_f32_16x16x32_bf16 v[28:31], v[124:127], v[210:213], v[28:31]
	v_mfma_f32_16x16x32_bf16 v[24:27], v[136:139], v[210:213], v[24:27]
	v_mfma_f32_16x16x32_bf16 v[12:15], v[124:127], v[218:221], v[12:15]
	v_mfma_f32_16x16x32_bf16 v[8:11], v[136:139], v[218:221], v[8:11]
	v_mfma_f32_16x16x32_bf16 v[60:63], v[132:135], v[198:201], v[60:63]
	v_mfma_f32_16x16x32_bf16 v[56:59], v[140:143], v[198:201], v[56:59]
	v_mfma_f32_16x16x32_bf16 v[44:47], v[132:135], v[206:209], v[44:47]
	v_mfma_f32_16x16x32_bf16 v[40:43], v[140:143], v[206:209], v[40:43]
	v_mfma_f32_16x16x32_bf16 v[28:31], v[132:135], v[214:217], v[28:31]
	v_mfma_f32_16x16x32_bf16 v[24:27], v[140:143], v[214:217], v[24:27]
	v_mfma_f32_16x16x32_bf16 v[12:15], v[132:135], v[222:225], v[12:15]
	v_mfma_f32_16x16x32_bf16 v[8:11], v[140:143], v[222:225], v[8:11]
	s_setprio 0
	s_setprio 0
	v_mfma_f32_16x16x32_bf16 v[52:55], v[162:165], v[194:197], v[52:55]
	v_mfma_f32_16x16x32_bf16 v[48:51], v[186:189], v[194:197], v[48:51]
	v_mfma_f32_16x16x32_bf16 v[36:39], v[162:165], v[202:205], v[36:39]
	v_mfma_f32_16x16x32_bf16 v[32:35], v[186:189], v[202:205], v[32:35]
	v_mfma_f32_16x16x32_bf16 v[20:23], v[162:165], v[210:213], v[20:23]
	v_mfma_f32_16x16x32_bf16 v[16:19], v[186:189], v[210:213], v[16:19]
	v_mfma_f32_16x16x32_bf16 v[4:7], v[162:165], v[218:221], v[4:7]
	v_mfma_f32_16x16x32_bf16 v[0:3], v[186:189], v[218:221], v[0:3]
	v_mfma_f32_16x16x32_bf16 v[52:55], v[182:185], v[198:201], v[52:55]
	v_mfma_f32_16x16x32_bf16 v[48:51], v[190:193], v[198:201], v[48:51]
	v_mfma_f32_16x16x32_bf16 v[36:39], v[182:185], v[206:209], v[36:39]
	v_mfma_f32_16x16x32_bf16 v[32:35], v[190:193], v[206:209], v[32:35]
	v_mfma_f32_16x16x32_bf16 v[20:23], v[182:185], v[214:217], v[20:23]
	v_mfma_f32_16x16x32_bf16 v[16:19], v[190:193], v[214:217], v[16:19]
	v_mfma_f32_16x16x32_bf16 v[4:7], v[182:185], v[222:225], v[4:7]
	v_mfma_f32_16x16x32_bf16 v[0:3], v[190:193], v[222:225], v[0:3]
	s_setprio 0
	s_barrier
	s_add_i32 s56, 0, 0x18000
	s_add_i32 s57, 0, 0x1c000
	v_add_u32_e32 v140, s56, v167
	v_add_u32_e32 v160, s57, v167
	ds_read_b128 v[124:127], v140
	ds_read_b128 v[132:135], v140 offset:1024
	ds_read_b128 v[136:139], v140 offset:2048
	ds_read_b128 v[140:143], v140 offset:3072
	ds_read_b128 v[162:165], v160
	ds_read_b128 v[182:185], v160 offset:1024
	ds_read_b128 v[186:189], v160 offset:2048
	ds_read_b128 v[190:193], v160 offset:3072
	s_add_u32 s28, s28, 0x40000
	s_addc_u32 s29, s29, 0
	s_mov_b32 m0, s37
	v_lshl_add_u64 v[230:231], s[28:29], 0, v[150:151]
	ds_read_b128 v[194:197], v179 offset:32768
	ds_read_b128 v[198:201], v179 offset:33792
	ds_read_b128 v[202:205], v179 offset:34816
	ds_read_b128 v[206:209], v179 offset:35840
	ds_read_b128 v[210:213], v179 offset:36864
	ds_read_b128 v[214:217], v179 offset:37888
	ds_read_b128 v[218:221], v179 offset:38912
	ds_read_b128 v[222:225], v179 offset:39936
	global_load_lds_dwordx4 v[230:231], off
	v_lshl_add_u64 v[230:231], s[28:29], 0, v[146:147]
	s_mov_b32 m0, s38
	s_nop 0
	global_load_lds_dwordx4 v[230:231], off
	s_waitcnt vmcnt(8)
	s_waitcnt lgkmcnt(0)
	s_barrier
	s_setprio 0
	s_waitcnt lgkmcnt(0)
	v_mfma_f32_16x16x32_bf16 v[128:131], v[124:127], v[194:197], v[128:131]
	v_mfma_f32_16x16x32_bf16 v[120:123], v[136:139], v[194:197], v[120:123]
	v_mfma_f32_16x16x32_bf16 v[108:111], v[124:127], v[202:205], v[108:111]
	v_mfma_f32_16x16x32_bf16 v[104:107], v[136:139], v[202:205], v[104:107]
	v_mfma_f32_16x16x32_bf16 v[92:95], v[124:127], v[210:213], v[92:95]
	v_mfma_f32_16x16x32_bf16 v[88:91], v[136:139], v[210:213], v[88:91]
	v_mfma_f32_16x16x32_bf16 v[76:79], v[124:127], v[218:221], v[76:79]
	v_mfma_f32_16x16x32_bf16 v[72:75], v[136:139], v[218:221], v[72:75]
	v_mfma_f32_16x16x32_bf16 v[128:131], v[132:135], v[198:201], v[128:131]
	v_mfma_f32_16x16x32_bf16 v[120:123], v[140:143], v[198:201], v[120:123]
	v_mfma_f32_16x16x32_bf16 v[108:111], v[132:135], v[206:209], v[108:111]
	v_mfma_f32_16x16x32_bf16 v[104:107], v[140:143], v[206:209], v[104:107]
	v_mfma_f32_16x16x32_bf16 v[92:95], v[132:135], v[214:217], v[92:95]
	v_mfma_f32_16x16x32_bf16 v[88:91], v[140:143], v[214:217], v[88:91]
	v_mfma_f32_16x16x32_bf16 v[76:79], v[132:135], v[222:225], v[76:79]
	v_mfma_f32_16x16x32_bf16 v[72:75], v[140:143], v[222:225], v[72:75]
	s_setprio 0
	s_setprio 0
	v_mfma_f32_16x16x32_bf16 v[116:119], v[162:165], v[194:197], v[116:119]
	v_mfma_f32_16x16x32_bf16 v[112:115], v[186:189], v[194:197], v[112:115]
	v_mfma_f32_16x16x32_bf16 v[100:103], v[162:165], v[202:205], v[100:103]
	v_mfma_f32_16x16x32_bf16 v[96:99], v[186:189], v[202:205], v[96:99]
	v_mfma_f32_16x16x32_bf16 v[84:87], v[162:165], v[210:213], v[84:87]
	v_mfma_f32_16x16x32_bf16 v[80:83], v[186:189], v[210:213], v[80:83]
	v_mfma_f32_16x16x32_bf16 v[68:71], v[162:165], v[218:221], v[68:71]
	v_mfma_f32_16x16x32_bf16 v[64:67], v[186:189], v[218:221], v[64:67]
	v_mfma_f32_16x16x32_bf16 v[116:119], v[182:185], v[198:201], v[116:119]
	v_mfma_f32_16x16x32_bf16 v[112:115], v[190:193], v[198:201], v[112:115]
	v_mfma_f32_16x16x32_bf16 v[100:103], v[182:185], v[206:209], v[100:103]
	v_mfma_f32_16x16x32_bf16 v[96:99], v[190:193], v[206:209], v[96:99]
	v_mfma_f32_16x16x32_bf16 v[84:87], v[182:185], v[214:217], v[84:87]
	v_mfma_f32_16x16x32_bf16 v[80:83], v[190:193], v[214:217], v[80:83]
	v_mfma_f32_16x16x32_bf16 v[68:71], v[182:185], v[222:225], v[68:71]
	v_mfma_f32_16x16x32_bf16 v[64:67], v[190:193], v[222:225], v[64:67]
	s_setprio 0
	s_barrier
	s_add_i32 s28, s56, s33
	v_lshl_add_u64 v[172:173], v[172:173], 0, s[10:11]
	s_mov_b32 m0, s28
	ds_read_b128 v[194:197], v179 offset:49152
	ds_read_b128 v[198:201], v179 offset:50176
	ds_read_b128 v[202:205], v179 offset:51200
	ds_read_b128 v[206:209], v179 offset:52224
	ds_read_b128 v[210:213], v179 offset:53248
	ds_read_b128 v[214:217], v179 offset:54272
	ds_read_b128 v[218:221], v179 offset:55296
	ds_read_b128 v[222:225], v179 offset:56320
	global_load_lds_dwordx4 v[172:173], off
	s_add_i32 m0, s28, 0x2000
	s_add_u32 s26, s26, 0x40080
	v_lshl_add_u64 v[172:173], v[176:177], 0, s[10:11]
	s_addc_u32 s27, s27, 0
	s_add_i32 s28, s57, s33
	global_load_lds_dwordx4 v[172:173], off
	v_lshl_add_u64 v[172:173], s[26:27], 0, v[148:149]
	s_mov_b32 m0, s28
	s_nop 0
	global_load_lds_dwordx4 v[172:173], off
	v_lshl_add_u64 v[172:173], s[26:27], 0, v[144:145]
	s_add_i32 m0, s28, 0x2000
	s_nop 0
	global_load_lds_dwordx4 v[172:173], off
	v_lshl_add_u64 v[172:173], v[226:227], 0, s[10:11]
	s_mov_b32 m0, s43
	s_nop 0
	global_load_lds_dwordx4 v[172:173], off
	v_lshl_add_u64 v[172:173], v[228:229], 0, s[10:11]
	s_mov_b32 m0, s44
	s_nop 0
	global_load_lds_dwordx4 v[172:173], off
	s_waitcnt vmcnt(8)
	s_waitcnt lgkmcnt(0)
	s_barrier
	s_setprio 0
	s_waitcnt lgkmcnt(0)
	v_mfma_f32_16x16x32_bf16 v[60:63], v[124:127], v[194:197], v[60:63]
	v_mfma_f32_16x16x32_bf16 v[56:59], v[136:139], v[194:197], v[56:59]
	v_mfma_f32_16x16x32_bf16 v[44:47], v[124:127], v[202:205], v[44:47]
	v_mfma_f32_16x16x32_bf16 v[40:43], v[136:139], v[202:205], v[40:43]
	v_mfma_f32_16x16x32_bf16 v[28:31], v[124:127], v[210:213], v[28:31]
	v_mfma_f32_16x16x32_bf16 v[24:27], v[136:139], v[210:213], v[24:27]
	v_mfma_f32_16x16x32_bf16 v[12:15], v[124:127], v[218:221], v[12:15]
	v_mfma_f32_16x16x32_bf16 v[8:11], v[136:139], v[218:221], v[8:11]
	v_mfma_f32_16x16x32_bf16 v[60:63], v[132:135], v[198:201], v[60:63]
	v_mfma_f32_16x16x32_bf16 v[56:59], v[140:143], v[198:201], v[56:59]
	v_mfma_f32_16x16x32_bf16 v[44:47], v[132:135], v[206:209], v[44:47]
	v_mfma_f32_16x16x32_bf16 v[40:43], v[140:143], v[206:209], v[40:43]
	v_mfma_f32_16x16x32_bf16 v[28:31], v[132:135], v[214:217], v[28:31]
	v_mfma_f32_16x16x32_bf16 v[24:27], v[140:143], v[214:217], v[24:27]
	v_mfma_f32_16x16x32_bf16 v[12:15], v[132:135], v[222:225], v[12:15]
	v_mfma_f32_16x16x32_bf16 v[8:11], v[140:143], v[222:225], v[8:11]
	s_setprio 0
	s_setprio 0
	v_mfma_f32_16x16x32_bf16 v[52:55], v[162:165], v[194:197], v[52:55]
	v_mfma_f32_16x16x32_bf16 v[48:51], v[186:189], v[194:197], v[48:51]
	v_mfma_f32_16x16x32_bf16 v[36:39], v[162:165], v[202:205], v[36:39]
	v_mfma_f32_16x16x32_bf16 v[32:35], v[186:189], v[202:205], v[32:35]
	v_mfma_f32_16x16x32_bf16 v[20:23], v[162:165], v[210:213], v[20:23]
	v_mfma_f32_16x16x32_bf16 v[16:19], v[186:189], v[210:213], v[16:19]
	v_mfma_f32_16x16x32_bf16 v[4:7], v[162:165], v[218:221], v[4:7]
	v_mfma_f32_16x16x32_bf16 v[0:3], v[186:189], v[218:221], v[0:3]
	v_mfma_f32_16x16x32_bf16 v[52:55], v[182:185], v[198:201], v[52:55]
	v_mfma_f32_16x16x32_bf16 v[48:51], v[190:193], v[198:201], v[48:51]
	v_mfma_f32_16x16x32_bf16 v[36:39], v[182:185], v[206:209], v[36:39]
	v_mfma_f32_16x16x32_bf16 v[32:35], v[190:193], v[206:209], v[32:35]
	v_mfma_f32_16x16x32_bf16 v[20:23], v[182:185], v[214:217], v[20:23]
	v_mfma_f32_16x16x32_bf16 v[16:19], v[190:193], v[214:217], v[16:19]
	v_mfma_f32_16x16x32_bf16 v[4:7], v[182:185], v[222:225], v[4:7]
	v_mfma_f32_16x16x32_bf16 v[0:3], v[190:193], v[222:225], v[0:3]
	s_setprio 0
	s_barrier
	s_add_i32 s55, s55, 2
	s_add_u32 s24, s24, 0x100
	s_addc_u32 s25, s25, 0
	s_add_u32 s53, s53, 0x100
	s_addc_u32 s54, s54, 0
	s_cmp_gt_u32 s55, 13
	s_cbranch_scc0 .LBB0_1113
	s_and_b64 vcc, exec, s[12:13]
	s_cbranch_vccz .LBB0_1116
	s_barrier

.LBB0_1196:
	ds_read_b128 v[144:147], v171
	ds_read_b128 v[148:151], v171 offset:1024
	ds_read_b128 v[152:155], v171 offset:2048
	ds_read_b128 v[156:159], v171 offset:3072
	ds_read_b128 v[160:163], v172
	ds_read_b128 v[164:167], v172 offset:1024
	ds_read_b128 v[174:177], v172 offset:2048
	ds_read_b128 v[178:181], v172 offset:3072
	s_add_u32 s16, s14, 0x100
	s_addc_u32 s17, s15, 0
	s_cmp_eq_u32 s43, 40
	s_cselect_b32 s21, s5, s17
	s_cselect_b32 s20, s4, s16
	s_cselect_b32 s19, s13, s42
	s_cselect_b32 s18, s12, s41
	v_lshl_add_u64 v[214:215], s[14:15], 0, v[136:137]
	s_add_i32 m0, s24, 0xc000
	ds_read_b128 v[182:185], v173
	ds_read_b128 v[186:189], v173 offset:1024
	ds_read_b128 v[190:193], v173 offset:2048
	ds_read_b128 v[194:197], v173 offset:3072
	ds_read_b128 v[198:201], v173 offset:4096
	ds_read_b128 v[202:205], v173 offset:5120
	ds_read_b128 v[206:209], v173 offset:6144
	ds_read_b128 v[210:213], v173 offset:7168
	global_load_lds_dwordx4 v[214:215], off
	v_lshl_add_u64 v[214:215], s[14:15], 0, v[138:139]
	s_add_i32 m0, s24, 0xe000
	s_nop 0
	global_load_lds_dwordx4 v[214:215], off
	s_waitcnt vmcnt(8)
	s_waitcnt lgkmcnt(0)
	s_barrier
	s_setprio 0
	s_waitcnt lgkmcnt(0)
	v_mfma_f32_16x16x32_bf16 v[124:127], v[144:147], v[182:185], v[124:127]
	v_mfma_f32_16x16x32_bf16 v[120:123], v[152:155], v[182:185], v[120:123]
	v_mfma_f32_16x16x32_bf16 v[112:115], v[144:147], v[190:193], v[112:115]
	v_mfma_f32_16x16x32_bf16 v[104:107], v[152:155], v[190:193], v[104:107]
	v_mfma_f32_16x16x32_bf16 v[96:99], v[144:147], v[198:201], v[96:99]
	v_mfma_f32_16x16x32_bf16 v[88:91], v[152:155], v[198:201], v[88:91]
	v_mfma_f32_16x16x32_bf16 v[80:83], v[144:147], v[206:209], v[80:83]
	v_mfma_f32_16x16x32_bf16 v[72:75], v[152:155], v[206:209], v[72:75]
	v_mfma_f32_16x16x32_bf16 v[124:127], v[148:151], v[186:189], v[124:127]
	v_mfma_f32_16x16x32_bf16 v[120:123], v[156:159], v[186:189], v[120:123]
	v_mfma_f32_16x16x32_bf16 v[112:115], v[148:151], v[194:197], v[112:115]
	v_mfma_f32_16x16x32_bf16 v[104:107], v[156:159], v[194:197], v[104:107]
	v_mfma_f32_16x16x32_bf16 v[96:99], v[148:151], v[202:205], v[96:99]
	v_mfma_f32_16x16x32_bf16 v[88:91], v[156:159], v[202:205], v[88:91]
	v_mfma_f32_16x16x32_bf16 v[80:83], v[148:151], v[210:213], v[80:83]
	v_mfma_f32_16x16x32_bf16 v[72:75], v[156:159], v[210:213], v[72:75]
	s_setprio 0
	s_setprio 0
	v_mfma_f32_16x16x32_bf16 v[116:119], v[160:163], v[182:185], v[116:119]
	v_mfma_f32_16x16x32_bf16 v[108:111], v[174:177], v[182:185], v[108:111]
	v_mfma_f32_16x16x32_bf16 v[100:103], v[160:163], v[190:193], v[100:103]
	v_mfma_f32_16x16x32_bf16 v[92:95], v[174:177], v[190:193], v[92:95]
	v_mfma_f32_16x16x32_bf16 v[84:87], v[160:163], v[198:201], v[84:87]
	v_mfma_f32_16x16x32_bf16 v[76:79], v[174:177], v[198:201], v[76:79]
	v_mfma_f32_16x16x32_bf16 v[68:71], v[160:163], v[206:209], v[68:71]
	v_mfma_f32_16x16x32_bf16 v[64:67], v[174:177], v[206:209], v[64:67]
	v_mfma_f32_16x16x32_bf16 v[116:119], v[164:167], v[186:189], v[116:119]
	v_mfma_f32_16x16x32_bf16 v[108:111], v[178:181], v[186:189], v[108:111]
	v_mfma_f32_16x16x32_bf16 v[100:103], v[164:167], v[194:197], v[100:103]
	v_mfma_f32_16x16x32_bf16 v[92:95], v[178:181], v[194:197], v[92:95]
	v_mfma_f32_16x16x32_bf16 v[84:87], v[164:167], v[202:205], v[84:87]
	v_mfma_f32_16x16x32_bf16 v[76:79], v[178:181], v[202:205], v[76:79]
	v_mfma_f32_16x16x32_bf16 v[68:71], v[164:167], v[210:213], v[68:71]
	v_mfma_f32_16x16x32_bf16 v[64:67], v[178:181], v[210:213], v[64:67]
	s_setprio 0
	s_barrier
	s_add_i32 s14, s35, s23
	v_lshl_add_u64 v[214:215], s[18:19], 0, v[130:131]
	s_mov_b32 m0, s14
	ds_read_b128 v[182:185], v173 offset:16384
	ds_read_b128 v[186:189], v173 offset:17408
	ds_read_b128 v[190:193], v173 offset:18432
	ds_read_b128 v[194:197], v173 offset:19456
	ds_read_b128 v[198:201], v173 offset:20480
	ds_read_b128 v[202:205], v173 offset:21504
	ds_read_b128 v[206:209], v173 offset:22528
	ds_read_b128 v[210:213], v173 offset:23552
	global_load_lds_dwordx4 v[214:215], off
	s_add_i32 m0, s14, 0x2000
	s_add_u32 s14, s18, 0xb0000
	v_lshl_add_u64 v[216:217], s[18:19], 0, v[134:135]
	s_addc_u32 s15, s19, 0
	s_add_i32 s44, s36, s23
	global_load_lds_dwordx4 v[216:217], off
	v_lshl_add_u64 v[218:219], s[14:15], 0, v[130:131]
	s_mov_b32 m0, s44
	v_lshl_add_u64 v[220:221], s[20:21], 0, v[132:133]
	global_load_lds_dwordx4 v[218:219], off
	v_lshl_add_u64 v[218:219], s[14:15], 0, v[134:135]
	s_add_i32 m0, s44, 0x2000
	s_nop 0
	global_load_lds_dwordx4 v[218:219], off
	v_lshl_add_u64 v[218:219], s[20:21], 0, v[128:129]
	s_mov_b32 m0, s24
	s_nop 0
	global_load_lds_dwordx4 v[218:219], off
	s_mov_b32 m0, s25
	s_nop 0
	global_load_lds_dwordx4 v[220:221], off
	s_waitcnt vmcnt(8)
	s_waitcnt lgkmcnt(0)
	s_barrier
	s_setprio 0
	s_waitcnt lgkmcnt(0)
	v_mfma_f32_16x16x32_bf16 v[60:63], v[144:147], v[182:185], v[60:63]
	v_mfma_f32_16x16x32_bf16 v[56:59], v[152:155], v[182:185], v[56:59]
	v_mfma_f32_16x16x32_bf16 v[48:51], v[144:147], v[190:193], v[48:51]
	v_mfma_f32_16x16x32_bf16 v[40:43], v[152:155], v[190:193], v[40:43]
	v_mfma_f32_16x16x32_bf16 v[32:35], v[144:147], v[198:201], v[32:35]
	v_mfma_f32_16x16x32_bf16 v[24:27], v[152:155], v[198:201], v[24:27]
	v_mfma_f32_16x16x32_bf16 v[16:19], v[144:147], v[206:209], v[16:19]
	v_mfma_f32_16x16x32_bf16 v[8:11], v[152:155], v[206:209], v[8:11]
	v_mfma_f32_16x16x32_bf16 v[60:63], v[148:151], v[186:189], v[60:63]
	v_mfma_f32_16x16x32_bf16 v[56:59], v[156:159], v[186:189], v[56:59]
	v_mfma_f32_16x16x32_bf16 v[48:51], v[148:151], v[194:197], v[48:51]
	v_mfma_f32_16x16x32_bf16 v[40:43], v[156:159], v[194:197], v[40:43]
	v_mfma_f32_16x16x32_bf16 v[32:35], v[148:151], v[202:205], v[32:35]
	v_mfma_f32_16x16x32_bf16 v[24:27], v[156:159], v[202:205], v[24:27]
	v_mfma_f32_16x16x32_bf16 v[16:19], v[148:151], v[210:213], v[16:19]
	v_mfma_f32_16x16x32_bf16 v[8:11], v[156:159], v[210:213], v[8:11]
	s_setprio 0
	s_setprio 0
	v_mfma_f32_16x16x32_bf16 v[52:55], v[160:163], v[182:185], v[52:55]
	v_mfma_f32_16x16x32_bf16 v[44:47], v[174:177], v[182:185], v[44:47]
	v_mfma_f32_16x16x32_bf16 v[36:39], v[160:163], v[190:193], v[36:39]
	v_mfma_f32_16x16x32_bf16 v[28:31], v[174:177], v[190:193], v[28:31]
	v_mfma_f32_16x16x32_bf16 v[20:23], v[160:163], v[198:201], v[20:23]
	v_mfma_f32_16x16x32_bf16 v[12:15], v[174:177], v[198:201], v[12:15]
	v_mfma_f32_16x16x32_bf16 v[4:7], v[160:163], v[206:209], v[4:7]
	v_mfma_f32_16x16x32_bf16 v[0:3], v[174:177], v[206:209], v[0:3]
	v_mfma_f32_16x16x32_bf16 v[52:55], v[164:167], v[186:189], v[52:55]
	v_mfma_f32_16x16x32_bf16 v[44:47], v[178:181], v[186:189], v[44:47]
	v_mfma_f32_16x16x32_bf16 v[36:39], v[164:167], v[194:197], v[36:39]
	v_mfma_f32_16x16x32_bf16 v[28:31], v[178:181], v[194:197], v[28:31]
	v_mfma_f32_16x16x32_bf16 v[20:23], v[164:167], v[202:205], v[20:23]
	v_mfma_f32_16x16x32_bf16 v[12:15], v[178:181], v[202:205], v[12:15]
	v_mfma_f32_16x16x32_bf16 v[4:7], v[164:167], v[210:213], v[4:7]
	v_mfma_f32_16x16x32_bf16 v[0:3], v[178:181], v[210:213], v[0:3]
	s_setprio 0
	s_barrier
	s_add_i32 s44, 0, 0x18000
	s_add_i32 s45, 0, 0x1c000
	v_add_u32_e32 v156, s44, v169
	v_add_u32_e32 v178, s45, v169
	ds_read_b128 v[144:147], v156
	ds_read_b128 v[148:151], v156 offset:1024
	ds_read_b128 v[152:155], v156 offset:2048
	ds_read_b128 v[156:159], v156 offset:3072
	ds_read_b128 v[160:163], v178
	ds_read_b128 v[164:167], v178 offset:1024
	ds_read_b128 v[174:177], v178 offset:2048
	ds_read_b128 v[178:181], v178 offset:3072
	s_add_u32 s14, s20, 0xb0000
	s_addc_u32 s15, s21, 0
	s_mov_b32 m0, s26
	v_lshl_add_u64 v[222:223], s[14:15], 0, v[128:129]
	ds_read_b128 v[182:185], v173 offset:32768
	ds_read_b128 v[186:189], v173 offset:33792
	ds_read_b128 v[190:193], v173 offset:34816
	ds_read_b128 v[194:197], v173 offset:35840
	ds_read_b128 v[198:201], v173 offset:36864
	ds_read_b128 v[202:205], v173 offset:37888
	ds_read_b128 v[206:209], v173 offset:38912
	ds_read_b128 v[210:213], v173 offset:39936
	global_load_lds_dwordx4 v[222:223], off
	v_lshl_add_u64 v[222:223], s[14:15], 0, v[132:133]
	s_mov_b32 m0, s27
	s_nop 0
	global_load_lds_dwordx4 v[222:223], off
	s_waitcnt vmcnt(8)
	s_waitcnt lgkmcnt(0)
	s_barrier
	s_setprio 0
	s_waitcnt lgkmcnt(0)
	v_mfma_f32_16x16x32_bf16 v[124:127], v[144:147], v[182:185], v[124:127]
	v_mfma_f32_16x16x32_bf16 v[120:123], v[152:155], v[182:185], v[120:123]
	v_mfma_f32_16x16x32_bf16 v[112:115], v[144:147], v[190:193], v[112:115]
	v_mfma_f32_16x16x32_bf16 v[104:107], v[152:155], v[190:193], v[104:107]
	v_mfma_f32_16x16x32_bf16 v[96:99], v[144:147], v[198:201], v[96:99]
	v_mfma_f32_16x16x32_bf16 v[88:91], v[152:155], v[198:201], v[88:91]
	v_mfma_f32_16x16x32_bf16 v[80:83], v[144:147], v[206:209], v[80:83]
	v_mfma_f32_16x16x32_bf16 v[72:75], v[152:155], v[206:209], v[72:75]
	v_mfma_f32_16x16x32_bf16 v[124:127], v[148:151], v[186:189], v[124:127]
	v_mfma_f32_16x16x32_bf16 v[120:123], v[156:159], v[186:189], v[120:123]
	v_mfma_f32_16x16x32_bf16 v[112:115], v[148:151], v[194:197], v[112:115]
	v_mfma_f32_16x16x32_bf16 v[104:107], v[156:159], v[194:197], v[104:107]
	v_mfma_f32_16x16x32_bf16 v[96:99], v[148:151], v[202:205], v[96:99]
	v_mfma_f32_16x16x32_bf16 v[88:91], v[156:159], v[202:205], v[88:91]
	v_mfma_f32_16x16x32_bf16 v[80:83], v[148:151], v[210:213], v[80:83]
	v_mfma_f32_16x16x32_bf16 v[72:75], v[156:159], v[210:213], v[72:75]
	s_setprio 0
	s_setprio 0
	v_mfma_f32_16x16x32_bf16 v[116:119], v[160:163], v[182:185], v[116:119]
	v_mfma_f32_16x16x32_bf16 v[108:111], v[174:177], v[182:185], v[108:111]
	v_mfma_f32_16x16x32_bf16 v[100:103], v[160:163], v[190:193], v[100:103]
	v_mfma_f32_16x16x32_bf16 v[92:95], v[174:177], v[190:193], v[92:95]
	v_mfma_f32_16x16x32_bf16 v[84:87], v[160:163], v[198:201], v[84:87]
	v_mfma_f32_16x16x32_bf16 v[76:79], v[174:177], v[198:201], v[76:79]
	v_mfma_f32_16x16x32_bf16 v[68:71], v[160:163], v[206:209], v[68:71]
	v_mfma_f32_16x16x32_bf16 v[64:67], v[174:177], v[206:209], v[64:67]
	v_mfma_f32_16x16x32_bf16 v[116:119], v[164:167], v[186:189], v[116:119]
	v_mfma_f32_16x16x32_bf16 v[108:111], v[178:181], v[186:189], v[108:111]
	v_mfma_f32_16x16x32_bf16 v[100:103], v[164:167], v[194:197], v[100:103]
	v_mfma_f32_16x16x32_bf16 v[92:95], v[178:181], v[194:197], v[92:95]
	v_mfma_f32_16x16x32_bf16 v[84:87], v[164:167], v[202:205], v[84:87]
	v_mfma_f32_16x16x32_bf16 v[76:79], v[178:181], v[202:205], v[76:79]
	v_mfma_f32_16x16x32_bf16 v[68:71], v[164:167], v[210:213], v[68:71]
	v_mfma_f32_16x16x32_bf16 v[64:67], v[178:181], v[210:213], v[64:67]
	s_setprio 0
	s_barrier
	s_add_i32 s14, s44, s23
	v_lshl_add_u64 v[214:215], v[214:215], 0, s[8:9]
	s_mov_b32 m0, s14
	ds_read_b128 v[182:185], v173 offset:49152
	ds_read_b128 v[186:189], v173 offset:50176
	ds_read_b128 v[190:193], v173 offset:51200
	ds_read_b128 v[194:197], v173 offset:52224
	ds_read_b128 v[198:201], v173 offset:53248
	ds_read_b128 v[202:205], v173 offset:54272
	ds_read_b128 v[206:209], v173 offset:55296
	ds_read_b128 v[210:213], v173 offset:56320
	global_load_lds_dwordx4 v[214:215], off
	s_add_i32 m0, s14, 0x2000
	s_add_u32 s14, s18, 0xb0080
	v_lshl_add_u64 v[214:215], v[216:217], 0, s[8:9]
	s_addc_u32 s15, s19, 0
	s_add_i32 s18, s45, s23
	global_load_lds_dwordx4 v[214:215], off
	v_lshl_add_u64 v[214:215], s[14:15], 0, v[130:131]
	s_mov_b32 m0, s18
	s_nop 0
	global_load_lds_dwordx4 v[214:215], off
	v_lshl_add_u64 v[214:215], s[14:15], 0, v[134:135]
	s_add_i32 m0, s18, 0x2000
	s_nop 0
	global_load_lds_dwordx4 v[214:215], off
	v_lshl_add_u64 v[214:215], v[218:219], 0, s[8:9]
	s_mov_b32 m0, s31
	s_nop 0
	global_load_lds_dwordx4 v[214:215], off
	v_lshl_add_u64 v[214:215], v[220:221], 0, s[8:9]
	s_mov_b32 m0, s33
	s_nop 0
	global_load_lds_dwordx4 v[214:215], off
	s_waitcnt vmcnt(8)
	s_waitcnt lgkmcnt(0)
	s_barrier
	s_setprio 0
	s_waitcnt lgkmcnt(0)
	v_mfma_f32_16x16x32_bf16 v[60:63], v[144:147], v[182:185], v[60:63]
	v_mfma_f32_16x16x32_bf16 v[56:59], v[152:155], v[182:185], v[56:59]
	v_mfma_f32_16x16x32_bf16 v[48:51], v[144:147], v[190:193], v[48:51]
	v_mfma_f32_16x16x32_bf16 v[40:43], v[152:155], v[190:193], v[40:43]
	v_mfma_f32_16x16x32_bf16 v[32:35], v[144:147], v[198:201], v[32:35]
	v_mfma_f32_16x16x32_bf16 v[24:27], v[152:155], v[198:201], v[24:27]
	v_mfma_f32_16x16x32_bf16 v[16:19], v[144:147], v[206:209], v[16:19]
	v_mfma_f32_16x16x32_bf16 v[8:11], v[152:155], v[206:209], v[8:11]
	v_mfma_f32_16x16x32_bf16 v[60:63], v[148:151], v[186:189], v[60:63]
	v_mfma_f32_16x16x32_bf16 v[56:59], v[156:159], v[186:189], v[56:59]
	v_mfma_f32_16x16x32_bf16 v[48:51], v[148:151], v[194:197], v[48:51]
	v_mfma_f32_16x16x32_bf16 v[40:43], v[156:159], v[194:197], v[40:43]
	v_mfma_f32_16x16x32_bf16 v[32:35], v[148:151], v[202:205], v[32:35]
	v_mfma_f32_16x16x32_bf16 v[24:27], v[156:159], v[202:205], v[24:27]
	v_mfma_f32_16x16x32_bf16 v[16:19], v[148:151], v[210:213], v[16:19]
	v_mfma_f32_16x16x32_bf16 v[8:11], v[156:159], v[210:213], v[8:11]
	s_setprio 0
	s_setprio 0
	v_mfma_f32_16x16x32_bf16 v[52:55], v[160:163], v[182:185], v[52:55]
	v_mfma_f32_16x16x32_bf16 v[44:47], v[174:177], v[182:185], v[44:47]
	v_mfma_f32_16x16x32_bf16 v[36:39], v[160:163], v[190:193], v[36:39]
	v_mfma_f32_16x16x32_bf16 v[28:31], v[174:177], v[190:193], v[28:31]
	v_mfma_f32_16x16x32_bf16 v[20:23], v[160:163], v[198:201], v[20:23]
	v_mfma_f32_16x16x32_bf16 v[12:15], v[174:177], v[198:201], v[12:15]
	v_mfma_f32_16x16x32_bf16 v[4:7], v[160:163], v[206:209], v[4:7]
	v_mfma_f32_16x16x32_bf16 v[0:3], v[174:177], v[206:209], v[0:3]
	v_mfma_f32_16x16x32_bf16 v[52:55], v[164:167], v[186:189], v[52:55]
	v_mfma_f32_16x16x32_bf16 v[44:47], v[178:181], v[186:189], v[44:47]
	v_mfma_f32_16x16x32_bf16 v[36:39], v[164:167], v[194:197], v[36:39]
	v_mfma_f32_16x16x32_bf16 v[28:31], v[178:181], v[194:197], v[28:31]
	v_mfma_f32_16x16x32_bf16 v[20:23], v[164:167], v[202:205], v[20:23]
	v_mfma_f32_16x16x32_bf16 v[12:15], v[178:181], v[202:205], v[12:15]
	v_mfma_f32_16x16x32_bf16 v[4:7], v[164:167], v[210:213], v[4:7]
	v_mfma_f32_16x16x32_bf16 v[0:3], v[178:181], v[210:213], v[0:3]
	s_setprio 0
	s_barrier
	s_add_i32 s43, s43, 2
	s_add_u32 s41, s41, 0x100
	s_addc_u32 s42, s42, 0
	s_cmp_gt_u32 s43, 41
	s_mov_b64 s[14:15], s[16:17]
	s_cbranch_scc0 .LBB0_1196
	s_and_b64 vcc, exec, s[10:11]
	s_cbranch_vccz .LBB0_1199
	s_barrier
